# GEMM K-loops: priority raised before the pre-MFMA barrier, redundant lgkmcnt(0) after it dropped, priority lowered after the end-of-segment barrier
# speedup vs baseline: 1.0054x; 1.0054x over previous
; #define PG8_STAGE(bufoff, gbase, voff) do { _Pragma("unroll") for (int _i = 0; _i < 2; ++_i) \
;         __builtin_amdgcn_global_load_lds((const unsigned*)((const char*)(gbase) + (voff)[_i]), (LAS unsigned*)(lds + (bufoff) + ldsw + _i * 8192), 16, 0, 0); } while (0)
; #define PG8_LDA(dst, b, h) do { _Pragma("unroll") for (int m = 0; m < 4; ++m) _Pragma("unroll") for (int k = 0; k < 2; ++k) dst[m][k] = *(const LAS bf16x8*)(lds + PG8_SA(b, h) + aoff + m * 2048 + k * 1024); } while (0)
; #define PG8_LDB(dst, b, h) do { _Pragma("unroll") for (int n = 0; n < 2; ++n) _Pragma("unroll") for (int k = 0; k < 2; ++k) dst[n][k] = *(const LAS bf16x8*)(lds + PG8_SB(b, h) + boff + n * 2048 + k * 1024); } while (0)
; #define PG8_WAIT_V(n) asm volatile("s_waitcnt vmcnt(" #n ")" ::: "memory")
; #define PG8_BAR __builtin_amdgcn_s_barrier()
; template <class Epi, bool SEG>
; __device__ __forceinline__ void gemm_phase(LAS unsigned char* lds, const Gemm g, const int G, const int cidx, const Epi& E) {
;     ...
;         for (int t = 0; t < nt; t += 2) {
;             const bool last = (t == nt - 2);
;             const char* a1 = cA + (size_t)(t + 1) * kstep;
;             const char* a2 = last ? nA : cA + (size_t)(t + 2) * kstep; const char* b2 = last ? nB : cB + (size_t)(t + 2) * kstep;
;             const char* a3 = a2 + kstep; const char* b3 = b2 + kstep;
;             PG8_LDB(B0, 0, 0); PG8_LDB(B1, 0, 1); PG8_SCHED; PG8_LDA(At, 0, 0); PG8_STAGE(PG8_SA(1, 1), a1 + hstepA, voffA);
;             PG8_WAIT_V(8); PG8_WAIT_L(0); PG8_BAR; PG8_MMA(0, 0, At, B0); PG8_MMA(0, 1, At, B1); PG8_BAR; PG8_SCHED;
;             PG8_LDA(At, 0, 1); PG8_STAGE(PG8_SB(0, 0), b2, voffB); PG8_STAGE(PG8_SB(0, 1), b2 + hstepB, voffB); PG8_STAGE(PG8_SA(0, 0), a2, voffA);
;             PG8_WAIT_V(8); PG8_WAIT_L(0); PG8_BAR; PG8_MMA(1, 0, At, B0); PG8_MMA(1, 1, At, B1); PG8_BAR; PG8_SCHED;
;             PG8_LDB(B0, 1, 0); PG8_LDB(B1, 1, 1); PG8_SCHED; PG8_LDA(At, 1, 0); PG8_STAGE(PG8_SA(0, 1), a2 + hstepA, voffA);
;             PG8_WAIT_V(8); PG8_WAIT_L(0); PG8_BAR; PG8_MMA(0, 0, At, B0); PG8_MMA(0, 1, At, B1); PG8_BAR; PG8_SCHED;
;             PG8_LDA(At, 1, 1); PG8_STAGE(PG8_SB(1, 0), b3, voffB); PG8_STAGE(PG8_SB(1, 1), b3 + hstepB, voffB); PG8_STAGE(PG8_SA(1, 0), a3, voffA);
;             PG8_WAIT_V(8); PG8_WAIT_L(0); PG8_BAR; PG8_MMA(1, 0, At, B0); PG8_MMA(1, 1, At, B1); PG8_BAR; PG8_SCHED;
.LBB0_294:
	s_add_u32 s48, s46, 0xfffc0080
	s_addc_u32 s49, s47, -1
	s_add_i32 s63, 0, 0x10000
	s_cmp_eq_u32 s62, 12
	s_cselect_b32 s51, s7, s49
	s_cselect_b32 s50, s23, s48
	s_cselect_b32 s49, s21, s61
	s_cselect_b32 s48, s59, s60
	s_add_i32 s66, 0, 0x14000
	v_add_u32_e32 v146, s63, v175
	v_add_u32_e32 v170, s66, v175
	ds_read_b128 v[134:137], v146
	ds_read_b128 v[138:141], v146 offset:1024
	ds_read_b128 v[142:145], v146 offset:2048
	ds_read_b128 v[146:149], v146 offset:3072
	ds_read_b128 v[158:161], v170
	ds_read_b128 v[162:165], v170 offset:1024
	ds_read_b128 v[166:169], v170 offset:2048
	ds_read_b128 v[170:173], v170 offset:3072
	v_lshl_add_u64 v[200:201], s[46:47], 0, v[154:155]
	s_add_i32 m0, s39, 0xc000
	ds_read_b128 v[180:183], v179
	ds_read_b128 v[184:187], v179 offset:1024
	ds_read_b128 v[188:191], v179 offset:2048
	ds_read_b128 v[192:195], v179 offset:3072
	ds_read_b128 v[196:199], v179 offset:4096
	ds_read_b128 v[212:215], v179 offset:5120
	ds_read_b128 v[216:219], v179 offset:6144
	ds_read_b128 v[220:223], v179 offset:7168
	global_load_lds_dwordx4 v[200:201], off
	v_lshl_add_u64 v[200:201], s[46:47], 0, v[156:157]
	s_add_i32 m0, s39, 0xe000
	s_nop 0
	global_load_lds_dwordx4 v[200:201], off
	s_waitcnt vmcnt(8)
	s_waitcnt lgkmcnt(0)
	s_setprio 1
	s_barrier
	v_mfma_f32_16x16x32_bf16 v[130:133], v[134:137], v[180:183], v[130:133]
	v_mfma_f32_16x16x32_bf16 v[126:129], v[142:145], v[180:183], v[126:129]
	v_mfma_f32_16x16x32_bf16 v[118:121], v[134:137], v[188:191], v[118:121]
	v_mfma_f32_16x16x32_bf16 v[110:113], v[142:145], v[188:191], v[110:113]
	v_mfma_f32_16x16x32_bf16 v[102:105], v[134:137], v[196:199], v[102:105]
	v_mfma_f32_16x16x32_bf16 v[94:97], v[142:145], v[196:199], v[94:97]
	v_mfma_f32_16x16x32_bf16 v[86:89], v[134:137], v[216:219], v[86:89]
	v_mfma_f32_16x16x32_bf16 v[78:81], v[142:145], v[216:219], v[78:81]
	v_mfma_f32_16x16x32_bf16 v[130:133], v[138:141], v[184:187], v[130:133]
	v_mfma_f32_16x16x32_bf16 v[126:129], v[146:149], v[184:187], v[126:129]
	v_mfma_f32_16x16x32_bf16 v[118:121], v[138:141], v[192:195], v[118:121]
	v_mfma_f32_16x16x32_bf16 v[110:113], v[146:149], v[192:195], v[110:113]
	v_mfma_f32_16x16x32_bf16 v[102:105], v[138:141], v[212:215], v[102:105]
	v_mfma_f32_16x16x32_bf16 v[94:97], v[146:149], v[212:215], v[94:97]
	v_mfma_f32_16x16x32_bf16 v[86:89], v[138:141], v[220:223], v[86:89]
	v_mfma_f32_16x16x32_bf16 v[78:81], v[146:149], v[220:223], v[78:81]
	s_setprio 0
	s_setprio 1
	v_mfma_f32_16x16x32_bf16 v[122:125], v[158:161], v[180:183], v[122:125]
	v_mfma_f32_16x16x32_bf16 v[114:117], v[166:169], v[180:183], v[114:117]
	v_mfma_f32_16x16x32_bf16 v[106:109], v[158:161], v[188:191], v[106:109]
	v_mfma_f32_16x16x32_bf16 v[98:101], v[166:169], v[188:191], v[98:101]
	v_mfma_f32_16x16x32_bf16 v[90:93], v[158:161], v[196:199], v[90:93]
	v_mfma_f32_16x16x32_bf16 v[82:85], v[166:169], v[196:199], v[82:85]
	v_mfma_f32_16x16x32_bf16 v[74:77], v[158:161], v[216:219], v[74:77]
	v_mfma_f32_16x16x32_bf16 v[70:73], v[166:169], v[216:219], v[70:73]
	v_mfma_f32_16x16x32_bf16 v[122:125], v[162:165], v[184:187], v[122:125]
	v_mfma_f32_16x16x32_bf16 v[114:117], v[170:173], v[184:187], v[114:117]
	v_mfma_f32_16x16x32_bf16 v[106:109], v[162:165], v[192:195], v[106:109]
	v_mfma_f32_16x16x32_bf16 v[98:101], v[170:173], v[192:195], v[98:101]
	v_mfma_f32_16x16x32_bf16 v[90:93], v[162:165], v[212:215], v[90:93]
	v_mfma_f32_16x16x32_bf16 v[82:85], v[170:173], v[212:215], v[82:85]
	v_mfma_f32_16x16x32_bf16 v[74:77], v[162:165], v[220:223], v[74:77]
	v_mfma_f32_16x16x32_bf16 v[70:73], v[170:173], v[220:223], v[70:73]
	s_barrier
	s_setprio 0
	s_add_i32 s63, s63, s1
	v_lshl_add_u64 v[200:201], s[48:49], 0, v[0:1]
	s_mov_b32 m0, s63
	ds_read_b128 v[180:183], v179 offset:16384
	ds_read_b128 v[184:187], v179 offset:17408
	ds_read_b128 v[188:191], v179 offset:18432
	ds_read_b128 v[192:195], v179 offset:19456
	ds_read_b128 v[196:199], v179 offset:20480
	ds_read_b128 v[212:215], v179 offset:21504
	ds_read_b128 v[216:219], v179 offset:22528
	ds_read_b128 v[220:223], v179 offset:23552
	global_load_lds_dwordx4 v[200:201], off
	s_add_i32 m0, s63, 0x2000
	s_add_u32 s64, s48, 0x40000
	v_lshl_add_u64 v[224:225], s[48:49], 0, v[14:15]
	s_addc_u32 s65, s49, 0
	s_add_i32 s63, s66, s1
	global_load_lds_dwordx4 v[224:225], off
	v_lshl_add_u64 v[226:227], s[64:65], 0, v[0:1]
	s_mov_b32 m0, s63
	v_lshl_add_u64 v[228:229], s[50:51], 0, v[150:151]
	global_load_lds_dwordx4 v[226:227], off
	v_lshl_add_u64 v[226:227], s[64:65], 0, v[14:15]
	s_add_i32 m0, s63, 0x2000
	s_nop 0
	global_load_lds_dwordx4 v[226:227], off
	v_lshl_add_u64 v[226:227], s[50:51], 0, v[152:153]
	s_mov_b32 m0, s39
	s_nop 0
	global_load_lds_dwordx4 v[226:227], off
	s_mov_b32 m0, s52
	s_nop 0
	global_load_lds_dwordx4 v[228:229], off
	s_waitcnt vmcnt(8)
	s_waitcnt lgkmcnt(0)
	s_setprio 1
	s_barrier
; #define PG8_STAGE(bufoff, gbase, voff) do { _Pragma("unroll") for (int _i = 0; _i < 2; ++_i) \
;         __builtin_amdgcn_global_load_lds((const unsigned*)((const char*)(gbase) + (voff)[_i]), (LAS unsigned*)(lds + (bufoff) + ldsw + _i * 8192), 16, 0, 0); } while (0)
; #define PG8_LDA(dst, b, h) do { _Pragma("unroll") for (int m = 0; m < 4; ++m) _Pragma("unroll") for (int k = 0; k < 2; ++k) dst[m][k] = *(const LAS bf16x8*)(lds + PG8_SA(b, h) + aoff + m * 2048 + k * 1024); } while (0)
; #define PG8_LDB(dst, b, h) do { _Pragma("unroll") for (int n = 0; n < 2; ++n) _Pragma("unroll") for (int k = 0; k < 2; ++k) dst[n][k] = *(const LAS bf16x8*)(lds + PG8_SB(b, h) + boff + n * 2048 + k * 1024); } while (0)
; #define PG8_MMA(ai, bj, At, Bt) do { __builtin_amdgcn_s_setprio(1); _Pragma("unroll") for (int m = 0; m < 4; ++m) _Pragma("unroll") for (int n = 0; n < 2; ++n) _Pragma("unroll") for (int k = 0; k < 2; ++k) \
;         acc[ai][bj][m][n] = __builtin_amdgcn_mfma_f32_16x16x32_bf16(Bt[n][k], At[m][k], acc[ai][bj][m][n], 0, 0, 0); __builtin_amdgcn_s_setprio(0); } while (0)
; #define PG8_WAIT_V(n) asm volatile("s_waitcnt vmcnt(" #n ")" ::: "memory")
; #define PG8_WAIT_L(n) asm volatile("s_waitcnt lgkmcnt(" #n ")" ::: "memory")
; #define PG8_BAR __builtin_amdgcn_s_barrier()
; #define PG8_SCHED __builtin_amdgcn_sched_barrier(0)
; template <class Epi, bool SEG>
; __device__ __forceinline__ void gemm_phase(LAS unsigned char* lds, const Gemm g, const int G, const int cidx, const Epi& E) {
;     ...
;             PG8_LDA(At, 0, 1); PG8_STAGE(PG8_SB(0, 0), b2, voffB); PG8_STAGE(PG8_SB(0, 1), b2 + hstepB, voffB); PG8_STAGE(PG8_SA(0, 0), a2, voffA);
;             PG8_WAIT_V(8); PG8_WAIT_L(0); PG8_BAR; PG8_MMA(1, 0, At, B0); PG8_MMA(1, 1, At, B1); PG8_BAR; PG8_SCHED;
;             PG8_LDB(B0, 1, 0); PG8_LDB(B1, 1, 1); PG8_SCHED; PG8_LDA(At, 1, 0); PG8_STAGE(PG8_SA(0, 1), a2 + hstepA, voffA);
;             PG8_WAIT_V(8); PG8_WAIT_L(0); PG8_BAR; PG8_MMA(0, 0, At, B0); PG8_MMA(0, 1, At, B1); PG8_BAR; PG8_SCHED;
;             PG8_LDA(At, 1, 1); PG8_STAGE(PG8_SB(1, 0), b3, voffB); PG8_STAGE(PG8_SB(1, 1), b3 + hstepB, voffB); PG8_STAGE(PG8_SA(1, 0), a3, voffA);
;             PG8_WAIT_V(8); PG8_WAIT_L(0); PG8_BAR; PG8_MMA(1, 0, At, B0); PG8_MMA(1, 1, At, B1); PG8_BAR; PG8_SCHED;
	v_mfma_f32_16x16x32_bf16 v[66:69], v[134:137], v[180:183], v[66:69]
	v_mfma_f32_16x16x32_bf16 v[62:65], v[142:145], v[180:183], v[62:65]
	v_mfma_f32_16x16x32_bf16 v[54:57], v[134:137], v[188:191], v[54:57]
	v_mfma_f32_16x16x32_bf16 v[46:49], v[142:145], v[188:191], v[46:49]
	v_mfma_f32_16x16x32_bf16 v[38:41], v[134:137], v[196:199], v[38:41]
	v_mfma_f32_16x16x32_bf16 v[30:33], v[142:145], v[196:199], v[30:33]
	v_mfma_f32_16x16x32_bf16 v[22:25], v[134:137], v[216:219], v[22:25]
	v_mfma_f32_16x16x32_bf16 v[10:13], v[142:145], v[216:219], v[10:13]
	v_mfma_f32_16x16x32_bf16 v[66:69], v[138:141], v[184:187], v[66:69]
	v_mfma_f32_16x16x32_bf16 v[62:65], v[146:149], v[184:187], v[62:65]
	v_mfma_f32_16x16x32_bf16 v[54:57], v[138:141], v[192:195], v[54:57]
	v_mfma_f32_16x16x32_bf16 v[46:49], v[146:149], v[192:195], v[46:49]
	v_mfma_f32_16x16x32_bf16 v[38:41], v[138:141], v[212:215], v[38:41]
	v_mfma_f32_16x16x32_bf16 v[30:33], v[146:149], v[212:215], v[30:33]
	v_mfma_f32_16x16x32_bf16 v[22:25], v[138:141], v[220:223], v[22:25]
	v_mfma_f32_16x16x32_bf16 v[10:13], v[146:149], v[220:223], v[10:13]
	s_setprio 0
	s_setprio 1
	v_mfma_f32_16x16x32_bf16 v[58:61], v[158:161], v[180:183], v[58:61]
	v_mfma_f32_16x16x32_bf16 v[50:53], v[166:169], v[180:183], v[50:53]
	v_mfma_f32_16x16x32_bf16 v[42:45], v[158:161], v[188:191], v[42:45]
	v_mfma_f32_16x16x32_bf16 v[34:37], v[166:169], v[188:191], v[34:37]
	v_mfma_f32_16x16x32_bf16 v[26:29], v[158:161], v[196:199], v[26:29]
	v_mfma_f32_16x16x32_bf16 v[18:21], v[166:169], v[196:199], v[18:21]
	v_mfma_f32_16x16x32_bf16 v[6:9], v[158:161], v[216:219], v[6:9]
	v_mfma_f32_16x16x32_bf16 v[2:5], v[166:169], v[216:219], v[2:5]
	v_mfma_f32_16x16x32_bf16 v[58:61], v[162:165], v[184:187], v[58:61]
	v_mfma_f32_16x16x32_bf16 v[50:53], v[170:173], v[184:187], v[50:53]
	v_mfma_f32_16x16x32_bf16 v[42:45], v[162:165], v[192:195], v[42:45]
	v_mfma_f32_16x16x32_bf16 v[34:37], v[170:173], v[192:195], v[34:37]
	v_mfma_f32_16x16x32_bf16 v[26:29], v[162:165], v[212:215], v[26:29]
	v_mfma_f32_16x16x32_bf16 v[18:21], v[170:173], v[212:215], v[18:21]
	v_mfma_f32_16x16x32_bf16 v[6:9], v[162:165], v[220:223], v[6:9]
	v_mfma_f32_16x16x32_bf16 v[2:5], v[170:173], v[220:223], v[2:5]
	s_barrier
	s_setprio 0
	s_add_i32 s63, 0, 0x18000
	s_add_i32 s64, 0, 0x1c000
	v_add_u32_e32 v146, s63, v175
	v_add_u32_e32 v170, s64, v175
	ds_read_b128 v[134:137], v146
	ds_read_b128 v[138:141], v146 offset:1024
	ds_read_b128 v[142:145], v146 offset:2048
	ds_read_b128 v[146:149], v146 offset:3072
	ds_read_b128 v[158:161], v170
	ds_read_b128 v[162:165], v170 offset:1024
	ds_read_b128 v[166:169], v170 offset:2048
	ds_read_b128 v[170:173], v170 offset:3072
	s_add_u32 s50, s50, 0x40000
	s_addc_u32 s51, s51, 0
	s_mov_b32 m0, s53
	v_lshl_add_u64 v[244:245], s[50:51], 0, v[152:153]
	ds_read_b128 v[180:183], v179 offset:32768
	ds_read_b128 v[184:187], v179 offset:33792
	ds_read_b128 v[188:191], v179 offset:34816
	ds_read_b128 v[192:195], v179 offset:35840
	ds_read_b128 v[196:199], v179 offset:36864
	ds_read_b128 v[212:215], v179 offset:37888
	ds_read_b128 v[216:219], v179 offset:38912
	ds_read_b128 v[220:223], v179 offset:39936
	global_load_lds_dwordx4 v[244:245], off
	v_lshl_add_u64 v[244:245], s[50:51], 0, v[150:151]
	s_mov_b32 m0, s54
	s_nop 0
	global_load_lds_dwordx4 v[244:245], off
	s_waitcnt vmcnt(8)
	s_waitcnt lgkmcnt(0)
	s_setprio 1
	s_barrier
	v_mfma_f32_16x16x32_bf16 v[130:133], v[134:137], v[180:183], v[130:133]
	v_mfma_f32_16x16x32_bf16 v[126:129], v[142:145], v[180:183], v[126:129]
	v_mfma_f32_16x16x32_bf16 v[118:121], v[134:137], v[188:191], v[118:121]
	v_mfma_f32_16x16x32_bf16 v[110:113], v[142:145], v[188:191], v[110:113]
	v_mfma_f32_16x16x32_bf16 v[102:105], v[134:137], v[196:199], v[102:105]
	v_mfma_f32_16x16x32_bf16 v[94:97], v[142:145], v[196:199], v[94:97]
	v_mfma_f32_16x16x32_bf16 v[86:89], v[134:137], v[216:219], v[86:89]
	v_mfma_f32_16x16x32_bf16 v[78:81], v[142:145], v[216:219], v[78:81]
	v_mfma_f32_16x16x32_bf16 v[130:133], v[138:141], v[184:187], v[130:133]
	v_mfma_f32_16x16x32_bf16 v[126:129], v[146:149], v[184:187], v[126:129]
	v_mfma_f32_16x16x32_bf16 v[118:121], v[138:141], v[192:195], v[118:121]
	v_mfma_f32_16x16x32_bf16 v[110:113], v[146:149], v[192:195], v[110:113]
	v_mfma_f32_16x16x32_bf16 v[102:105], v[138:141], v[212:215], v[102:105]
	v_mfma_f32_16x16x32_bf16 v[94:97], v[146:149], v[212:215], v[94:97]
	v_mfma_f32_16x16x32_bf16 v[86:89], v[138:141], v[220:223], v[86:89]
	v_mfma_f32_16x16x32_bf16 v[78:81], v[146:149], v[220:223], v[78:81]
	s_setprio 0
	s_setprio 1
	v_mfma_f32_16x16x32_bf16 v[122:125], v[158:161], v[180:183], v[122:125]
	v_mfma_f32_16x16x32_bf16 v[114:117], v[166:169], v[180:183], v[114:117]
	v_mfma_f32_16x16x32_bf16 v[106:109], v[158:161], v[188:191], v[106:109]
	v_mfma_f32_16x16x32_bf16 v[98:101], v[166:169], v[188:191], v[98:101]
	v_mfma_f32_16x16x32_bf16 v[90:93], v[158:161], v[196:199], v[90:93]
	v_mfma_f32_16x16x32_bf16 v[82:85], v[166:169], v[196:199], v[82:85]
	v_mfma_f32_16x16x32_bf16 v[74:77], v[158:161], v[216:219], v[74:77]
	v_mfma_f32_16x16x32_bf16 v[70:73], v[166:169], v[216:219], v[70:73]
	v_mfma_f32_16x16x32_bf16 v[122:125], v[162:165], v[184:187], v[122:125]
	v_mfma_f32_16x16x32_bf16 v[114:117], v[170:173], v[184:187], v[114:117]
	v_mfma_f32_16x16x32_bf16 v[106:109], v[162:165], v[192:195], v[106:109]
	v_mfma_f32_16x16x32_bf16 v[98:101], v[170:173], v[192:195], v[98:101]
	v_mfma_f32_16x16x32_bf16 v[90:93], v[162:165], v[212:215], v[90:93]
	v_mfma_f32_16x16x32_bf16 v[82:85], v[170:173], v[212:215], v[82:85]
	v_mfma_f32_16x16x32_bf16 v[74:77], v[162:165], v[220:223], v[74:77]
	v_mfma_f32_16x16x32_bf16 v[70:73], v[170:173], v[220:223], v[70:73]
	s_barrier
; #define PG8_STAGE(bufoff, gbase, voff) do { _Pragma("unroll") for (int _i = 0; _i < 2; ++_i) \
;         __builtin_amdgcn_global_load_lds((const unsigned*)((const char*)(gbase) + (voff)[_i]), (LAS unsigned*)(lds + (bufoff) + ldsw + _i * 8192), 16, 0, 0); } while (0)
; #define PG8_LDA(dst, b, h) do { _Pragma("unroll") for (int m = 0; m < 4; ++m) _Pragma("unroll") for (int k = 0; k < 2; ++k) dst[m][k] = *(const LAS bf16x8*)(lds + PG8_SA(b, h) + aoff + m * 2048 + k * 1024); } while (0)
; #define PG8_LDB(dst, b, h) do { _Pragma("unroll") for (int n = 0; n < 2; ++n) _Pragma("unroll") for (int k = 0; k < 2; ++k) dst[n][k] = *(const LAS bf16x8*)(lds + PG8_SB(b, h) + boff + n * 2048 + k * 1024); } while (0)
; #define PG8_MMA(ai, bj, At, Bt) do { __builtin_amdgcn_s_setprio(1); _Pragma("unroll") for (int m = 0; m < 4; ++m) _Pragma("unroll") for (int n = 0; n < 2; ++n) _Pragma("unroll") for (int k = 0; k < 2; ++k) \
;         acc[ai][bj][m][n] = __builtin_amdgcn_mfma_f32_16x16x32_bf16(Bt[n][k], At[m][k], acc[ai][bj][m][n], 0, 0, 0); __builtin_amdgcn_s_setprio(0); } while (0)
; #define PG8_WAIT_V(n) asm volatile("s_waitcnt vmcnt(" #n ")" ::: "memory")
; #define PG8_WAIT_L(n) asm volatile("s_waitcnt lgkmcnt(" #n ")" ::: "memory")
; #define PG8_BAR __builtin_amdgcn_s_barrier()
; #define PG8_SCHED __builtin_amdgcn_sched_barrier(0)
; template <class Epi, bool SEG>
; __device__ __forceinline__ void gemm_phase(LAS unsigned char* lds, const Gemm g, const int G, const int cidx, const Epi& E) {
;     ...
;             PG8_LDB(B0, 1, 0); PG8_LDB(B1, 1, 1); PG8_SCHED; PG8_LDA(At, 1, 0); PG8_STAGE(PG8_SA(0, 1), a2 + hstepA, voffA);
;             PG8_WAIT_V(8); PG8_WAIT_L(0); PG8_BAR; PG8_MMA(0, 0, At, B0); PG8_MMA(0, 1, At, B1); PG8_BAR; PG8_SCHED;
;             PG8_LDA(At, 1, 1); PG8_STAGE(PG8_SB(1, 0), b3, voffB); PG8_STAGE(PG8_SB(1, 1), b3 + hstepB, voffB); PG8_STAGE(PG8_SA(1, 0), a3, voffA);
;             PG8_WAIT_V(8); PG8_WAIT_L(0); PG8_BAR; PG8_MMA(1, 0, At, B0); PG8_MMA(1, 1, At, B1); PG8_BAR; PG8_SCHED;
;         }
;         if (wr == 0) PG8_BAR;
	s_setprio 0
	s_add_i32 s50, s63, s1
	v_lshl_add_u64 v[200:201], v[200:201], 0, s[28:29]
	s_mov_b32 m0, s50
	ds_read_b128 v[180:183], v179 offset:49152
	ds_read_b128 v[184:187], v179 offset:50176
	ds_read_b128 v[188:191], v179 offset:51200
	ds_read_b128 v[192:195], v179 offset:52224
	ds_read_b128 v[196:199], v179 offset:53248
	ds_read_b128 v[212:215], v179 offset:54272
	ds_read_b128 v[216:219], v179 offset:55296
	ds_read_b128 v[220:223], v179 offset:56320
	global_load_lds_dwordx4 v[200:201], off
	s_add_i32 m0, s50, 0x2000
	s_add_u32 s48, s48, 0x40080
	v_lshl_add_u64 v[200:201], v[224:225], 0, s[28:29]
	s_addc_u32 s49, s49, 0
	s_add_i32 s50, s64, s1
	global_load_lds_dwordx4 v[200:201], off
	v_lshl_add_u64 v[200:201], s[48:49], 0, v[0:1]
	s_mov_b32 m0, s50
	s_nop 0
	global_load_lds_dwordx4 v[200:201], off
	v_lshl_add_u64 v[200:201], s[48:49], 0, v[14:15]
	s_add_i32 m0, s50, 0x2000
	s_nop 0
	global_load_lds_dwordx4 v[200:201], off
	v_lshl_add_u64 v[200:201], v[226:227], 0, s[28:29]
	s_mov_b32 m0, s55
	s_nop 0
	global_load_lds_dwordx4 v[200:201], off
	v_lshl_add_u64 v[200:201], v[228:229], 0, s[28:29]
	s_mov_b32 m0, s56
	s_nop 0
	global_load_lds_dwordx4 v[200:201], off
	s_waitcnt vmcnt(8)
	s_waitcnt lgkmcnt(0)
	s_setprio 1
	s_barrier
	v_mfma_f32_16x16x32_bf16 v[66:69], v[134:137], v[180:183], v[66:69]
	v_mfma_f32_16x16x32_bf16 v[62:65], v[142:145], v[180:183], v[62:65]
	v_mfma_f32_16x16x32_bf16 v[54:57], v[134:137], v[188:191], v[54:57]
	v_mfma_f32_16x16x32_bf16 v[46:49], v[142:145], v[188:191], v[46:49]
	v_mfma_f32_16x16x32_bf16 v[38:41], v[134:137], v[196:199], v[38:41]
	v_mfma_f32_16x16x32_bf16 v[30:33], v[142:145], v[196:199], v[30:33]
	v_mfma_f32_16x16x32_bf16 v[22:25], v[134:137], v[216:219], v[22:25]
	v_mfma_f32_16x16x32_bf16 v[10:13], v[142:145], v[216:219], v[10:13]
	v_mfma_f32_16x16x32_bf16 v[66:69], v[138:141], v[184:187], v[66:69]
	v_mfma_f32_16x16x32_bf16 v[62:65], v[146:149], v[184:187], v[62:65]
	v_mfma_f32_16x16x32_bf16 v[54:57], v[138:141], v[192:195], v[54:57]
	v_mfma_f32_16x16x32_bf16 v[46:49], v[146:149], v[192:195], v[46:49]
	v_mfma_f32_16x16x32_bf16 v[38:41], v[138:141], v[212:215], v[38:41]
	v_mfma_f32_16x16x32_bf16 v[30:33], v[146:149], v[212:215], v[30:33]
	v_mfma_f32_16x16x32_bf16 v[22:25], v[138:141], v[220:223], v[22:25]
	v_mfma_f32_16x16x32_bf16 v[10:13], v[146:149], v[220:223], v[10:13]
	s_setprio 0
	s_setprio 1
	v_mfma_f32_16x16x32_bf16 v[58:61], v[158:161], v[180:183], v[58:61]
	v_mfma_f32_16x16x32_bf16 v[50:53], v[166:169], v[180:183], v[50:53]
	v_mfma_f32_16x16x32_bf16 v[42:45], v[158:161], v[188:191], v[42:45]
	v_mfma_f32_16x16x32_bf16 v[34:37], v[166:169], v[188:191], v[34:37]
	v_mfma_f32_16x16x32_bf16 v[26:29], v[158:161], v[196:199], v[26:29]
	v_mfma_f32_16x16x32_bf16 v[18:21], v[166:169], v[196:199], v[18:21]
	v_mfma_f32_16x16x32_bf16 v[6:9], v[158:161], v[216:219], v[6:9]
	v_mfma_f32_16x16x32_bf16 v[2:5], v[166:169], v[216:219], v[2:5]
	v_mfma_f32_16x16x32_bf16 v[58:61], v[162:165], v[184:187], v[58:61]
	v_mfma_f32_16x16x32_bf16 v[50:53], v[170:173], v[184:187], v[50:53]
	v_mfma_f32_16x16x32_bf16 v[42:45], v[162:165], v[192:195], v[42:45]
	v_mfma_f32_16x16x32_bf16 v[34:37], v[170:173], v[192:195], v[34:37]
	v_mfma_f32_16x16x32_bf16 v[26:29], v[162:165], v[212:215], v[26:29]
	v_mfma_f32_16x16x32_bf16 v[18:21], v[170:173], v[212:215], v[18:21]
	v_mfma_f32_16x16x32_bf16 v[6:9], v[162:165], v[220:223], v[6:9]
	v_mfma_f32_16x16x32_bf16 v[2:5], v[170:173], v[220:223], v[2:5]
	s_barrier
	s_setprio 0
	s_add_i32 s62, s62, 2
	s_add_u32 s46, s46, 0x100
	s_addc_u32 s47, s47, 0
	s_add_u32 s60, s60, 0x100
	s_addc_u32 s61, s61, 0
	s_cmp_gt_u32 s62, 13
	s_cbranch_scc0 .LBB0_294
	s_and_b64 vcc, exec, s[18:19]
	s_cbranch_vccz .LBB0_297
	s_barrier

; #define PG8_STAGE(bufoff, gbase, voff) do { _Pragma("unroll") for (int _i = 0; _i < 2; ++_i) \
;         __builtin_amdgcn_global_load_lds((const unsigned*)((const char*)(gbase) + (voff)[_i]), (LAS unsigned*)(lds + (bufoff) + ldsw + _i * 8192), 16, 0, 0); } while (0)
; #define PG8_LDA(dst, b, h) do { _Pragma("unroll") for (int m = 0; m < 4; ++m) _Pragma("unroll") for (int k = 0; k < 2; ++k) dst[m][k] = *(const LAS bf16x8*)(lds + PG8_SA(b, h) + aoff + m * 2048 + k * 1024); } while (0)
; #define PG8_LDB(dst, b, h) do { _Pragma("unroll") for (int n = 0; n < 2; ++n) _Pragma("unroll") for (int k = 0; k < 2; ++k) dst[n][k] = *(const LAS bf16x8*)(lds + PG8_SB(b, h) + boff + n * 2048 + k * 1024); } while (0)
; #define PG8_WAIT_V(n) asm volatile("s_waitcnt vmcnt(" #n ")" ::: "memory")
; #define PG8_BAR __builtin_amdgcn_s_barrier()
; template <class Epi, bool SEG>
; __device__ __forceinline__ void gemm_phase(LAS unsigned char* lds, const Gemm g, const int G, const int cidx, const Epi& E) {
;     ...
;         for (int t = 0; t < nt; t += 2) {
;             const bool last = (t == nt - 2);
;             const char* a1 = cA + (size_t)(t + 1) * kstep;
;             const char* a2 = last ? nA : cA + (size_t)(t + 2) * kstep; const char* b2 = last ? nB : cB + (size_t)(t + 2) * kstep;
;             const char* a3 = a2 + kstep; const char* b3 = b2 + kstep;
;             PG8_LDB(B0, 0, 0); PG8_LDB(B1, 0, 1); PG8_SCHED; PG8_LDA(At, 0, 0); PG8_STAGE(PG8_SA(1, 1), a1 + hstepA, voffA);
;             PG8_WAIT_V(8); PG8_WAIT_L(0); PG8_BAR; PG8_MMA(0, 0, At, B0); PG8_MMA(0, 1, At, B1); PG8_BAR; PG8_SCHED;
;             PG8_LDA(At, 0, 1); PG8_STAGE(PG8_SB(0, 0), b2, voffB); PG8_STAGE(PG8_SB(0, 1), b2 + hstepB, voffB); PG8_STAGE(PG8_SA(0, 0), a2, voffA);
;             PG8_WAIT_V(8); PG8_WAIT_L(0); PG8_BAR; PG8_MMA(1, 0, At, B0); PG8_MMA(1, 1, At, B1); PG8_BAR; PG8_SCHED;
;             PG8_LDB(B0, 1, 0); PG8_LDB(B1, 1, 1); PG8_SCHED; PG8_LDA(At, 1, 0); PG8_STAGE(PG8_SA(0, 1), a2 + hstepA, voffA);
;             PG8_WAIT_V(8); PG8_WAIT_L(0); PG8_BAR; PG8_MMA(0, 0, At, B0); PG8_MMA(0, 1, At, B1); PG8_BAR; PG8_SCHED;
;             PG8_LDA(At, 1, 1); PG8_STAGE(PG8_SB(1, 0), b3, voffB); PG8_STAGE(PG8_SB(1, 1), b3 + hstepB, voffB); PG8_STAGE(PG8_SA(1, 0), a3, voffA);
;             PG8_WAIT_V(8); PG8_WAIT_L(0); PG8_BAR; PG8_MMA(1, 0, At, B0); PG8_MMA(1, 1, At, B1); PG8_BAR; PG8_SCHED;
.LBB0_706:
	s_add_u32 s48, s40, 0xfffc0080
	s_addc_u32 s49, s41, -1
	s_add_i32 s59, 0, 0x10000
	s_cmp_eq_u32 s58, 12
	s_cselect_b32 s51, s19, s49
	s_cselect_b32 s50, s54, s48
	s_cselect_b32 s49, s17, s57
	s_cselect_b32 s48, s55, s56
	s_add_i32 s62, 0, 0x14000
	v_add_u32_e32 v146, s59, v228
	v_add_u32_e32 v162, s62, v228
	ds_read_b128 v[130:133], v146
	ds_read_b128 v[138:141], v146 offset:1024
	ds_read_b128 v[142:145], v146 offset:2048
	ds_read_b128 v[146:149], v146 offset:3072
	ds_read_b128 v[150:153], v162
	ds_read_b128 v[154:157], v162 offset:1024
	ds_read_b128 v[158:161], v162 offset:2048
	ds_read_b128 v[162:165], v162 offset:3072
	v_lshl_add_u64 v[216:217], s[40:41], 0, v[198:199]
	s_add_i32 m0, s30, 0xc000
	ds_read_b128 v[166:169], v244
	ds_read_b128 v[170:173], v244 offset:1024
	ds_read_b128 v[174:177], v244 offset:2048
	ds_read_b128 v[178:181], v244 offset:3072
	ds_read_b128 v[182:185], v244 offset:4096
	ds_read_b128 v[186:189], v244 offset:5120
	ds_read_b128 v[190:193], v244 offset:6144
	ds_read_b128 v[212:215], v244 offset:7168
	global_load_lds_dwordx4 v[216:217], off
	v_lshl_add_u64 v[216:217], s[40:41], 0, v[200:201]
	s_add_i32 m0, s30, 0xe000
	s_nop 0
	global_load_lds_dwordx4 v[216:217], off
	s_waitcnt vmcnt(8)
	s_waitcnt lgkmcnt(0)
	s_setprio 1
	s_barrier
	v_mfma_f32_16x16x32_bf16 v[134:137], v[130:133], v[166:169], v[134:137]
	v_mfma_f32_16x16x32_bf16 v[126:129], v[142:145], v[166:169], v[126:129]
	v_mfma_f32_16x16x32_bf16 v[114:117], v[130:133], v[174:177], v[114:117]
	v_mfma_f32_16x16x32_bf16 v[110:113], v[142:145], v[174:177], v[110:113]
	v_mfma_f32_16x16x32_bf16 v[98:101], v[130:133], v[182:185], v[98:101]
	v_mfma_f32_16x16x32_bf16 v[94:97], v[142:145], v[182:185], v[94:97]
	v_mfma_f32_16x16x32_bf16 v[82:85], v[130:133], v[190:193], v[82:85]
	v_mfma_f32_16x16x32_bf16 v[78:81], v[142:145], v[190:193], v[78:81]
	v_mfma_f32_16x16x32_bf16 v[134:137], v[138:141], v[170:173], v[134:137]
	v_mfma_f32_16x16x32_bf16 v[126:129], v[146:149], v[170:173], v[126:129]
	v_mfma_f32_16x16x32_bf16 v[114:117], v[138:141], v[178:181], v[114:117]
	v_mfma_f32_16x16x32_bf16 v[110:113], v[146:149], v[178:181], v[110:113]
	v_mfma_f32_16x16x32_bf16 v[98:101], v[138:141], v[186:189], v[98:101]
	v_mfma_f32_16x16x32_bf16 v[94:97], v[146:149], v[186:189], v[94:97]
	v_mfma_f32_16x16x32_bf16 v[82:85], v[138:141], v[212:215], v[82:85]
	v_mfma_f32_16x16x32_bf16 v[78:81], v[146:149], v[212:215], v[78:81]
	s_setprio 0
	s_setprio 1
	v_mfma_f32_16x16x32_bf16 v[122:125], v[150:153], v[166:169], v[122:125]
	v_mfma_f32_16x16x32_bf16 v[118:121], v[158:161], v[166:169], v[118:121]
	v_mfma_f32_16x16x32_bf16 v[106:109], v[150:153], v[174:177], v[106:109]
	v_mfma_f32_16x16x32_bf16 v[102:105], v[158:161], v[174:177], v[102:105]
	v_mfma_f32_16x16x32_bf16 v[90:93], v[150:153], v[182:185], v[90:93]
	v_mfma_f32_16x16x32_bf16 v[86:89], v[158:161], v[182:185], v[86:89]
	v_mfma_f32_16x16x32_bf16 v[74:77], v[150:153], v[190:193], v[74:77]
	v_mfma_f32_16x16x32_bf16 v[70:73], v[158:161], v[190:193], v[70:73]
	v_mfma_f32_16x16x32_bf16 v[122:125], v[154:157], v[170:173], v[122:125]
	v_mfma_f32_16x16x32_bf16 v[118:121], v[162:165], v[170:173], v[118:121]
	v_mfma_f32_16x16x32_bf16 v[106:109], v[154:157], v[178:181], v[106:109]
	v_mfma_f32_16x16x32_bf16 v[102:105], v[162:165], v[178:181], v[102:105]
	v_mfma_f32_16x16x32_bf16 v[90:93], v[154:157], v[186:189], v[90:93]
	v_mfma_f32_16x16x32_bf16 v[86:89], v[162:165], v[186:189], v[86:89]
	v_mfma_f32_16x16x32_bf16 v[74:77], v[154:157], v[212:215], v[74:77]
	v_mfma_f32_16x16x32_bf16 v[70:73], v[162:165], v[212:215], v[70:73]
	s_barrier
	s_setprio 0
	s_add_i32 s59, s59, s9
	v_lshl_add_u64 v[216:217], s[48:49], 0, v[0:1]
	s_mov_b32 m0, s59
	ds_read_b128 v[166:169], v244 offset:16384
	ds_read_b128 v[170:173], v244 offset:17408
	ds_read_b128 v[174:177], v244 offset:18432
	ds_read_b128 v[178:181], v244 offset:19456
	ds_read_b128 v[182:185], v244 offset:20480
	ds_read_b128 v[186:189], v244 offset:21504
	ds_read_b128 v[190:193], v244 offset:22528
	ds_read_b128 v[212:215], v244 offset:23552
	global_load_lds_dwordx4 v[216:217], off
	s_add_i32 m0, s59, 0x2000
	s_add_u32 s60, s48, 0x40000
	v_lshl_add_u64 v[218:219], s[48:49], 0, v[14:15]
	s_addc_u32 s61, s49, 0
	s_add_i32 s59, s62, s9
	global_load_lds_dwordx4 v[218:219], off
	v_lshl_add_u64 v[220:221], s[60:61], 0, v[0:1]
	s_mov_b32 m0, s59
	v_lshl_add_u64 v[222:223], s[50:51], 0, v[194:195]
	global_load_lds_dwordx4 v[220:221], off
	v_lshl_add_u64 v[220:221], s[60:61], 0, v[14:15]
	s_add_i32 m0, s59, 0x2000
	s_nop 0
	global_load_lds_dwordx4 v[220:221], off
	v_lshl_add_u64 v[220:221], s[50:51], 0, v[196:197]
	s_mov_b32 m0, s30
	s_nop 0
	global_load_lds_dwordx4 v[220:221], off
	s_mov_b32 m0, s31
	s_nop 0
	global_load_lds_dwordx4 v[222:223], off
	s_waitcnt vmcnt(8)
	s_waitcnt lgkmcnt(0)
	s_setprio 1
	s_barrier
; #define PG8_STAGE(bufoff, gbase, voff) do { _Pragma("unroll") for (int _i = 0; _i < 2; ++_i) \
;         __builtin_amdgcn_global_load_lds((const unsigned*)((const char*)(gbase) + (voff)[_i]), (LAS unsigned*)(lds + (bufoff) + ldsw + _i * 8192), 16, 0, 0); } while (0)
; #define PG8_LDA(dst, b, h) do { _Pragma("unroll") for (int m = 0; m < 4; ++m) _Pragma("unroll") for (int k = 0; k < 2; ++k) dst[m][k] = *(const LAS bf16x8*)(lds + PG8_SA(b, h) + aoff + m * 2048 + k * 1024); } while (0)
; #define PG8_LDB(dst, b, h) do { _Pragma("unroll") for (int n = 0; n < 2; ++n) _Pragma("unroll") for (int k = 0; k < 2; ++k) dst[n][k] = *(const LAS bf16x8*)(lds + PG8_SB(b, h) + boff + n * 2048 + k * 1024); } while (0)
; #define PG8_MMA(ai, bj, At, Bt) do { __builtin_amdgcn_s_setprio(1); _Pragma("unroll") for (int m = 0; m < 4; ++m) _Pragma("unroll") for (int n = 0; n < 2; ++n) _Pragma("unroll") for (int k = 0; k < 2; ++k) \
;         acc[ai][bj][m][n] = __builtin_amdgcn_mfma_f32_16x16x32_bf16(Bt[n][k], At[m][k], acc[ai][bj][m][n], 0, 0, 0); __builtin_amdgcn_s_setprio(0); } while (0)
; #define PG8_WAIT_V(n) asm volatile("s_waitcnt vmcnt(" #n ")" ::: "memory")
; #define PG8_WAIT_L(n) asm volatile("s_waitcnt lgkmcnt(" #n ")" ::: "memory")
; #define PG8_BAR __builtin_amdgcn_s_barrier()
; #define PG8_SCHED __builtin_amdgcn_sched_barrier(0)
; template <class Epi, bool SEG>
; __device__ __forceinline__ void gemm_phase(LAS unsigned char* lds, const Gemm g, const int G, const int cidx, const Epi& E) {
;     ...
;             PG8_LDA(At, 0, 1); PG8_STAGE(PG8_SB(0, 0), b2, voffB); PG8_STAGE(PG8_SB(0, 1), b2 + hstepB, voffB); PG8_STAGE(PG8_SA(0, 0), a2, voffA);
;             PG8_WAIT_V(8); PG8_WAIT_L(0); PG8_BAR; PG8_MMA(1, 0, At, B0); PG8_MMA(1, 1, At, B1); PG8_BAR; PG8_SCHED;
;             PG8_LDB(B0, 1, 0); PG8_LDB(B1, 1, 1); PG8_SCHED; PG8_LDA(At, 1, 0); PG8_STAGE(PG8_SA(0, 1), a2 + hstepA, voffA);
;             PG8_WAIT_V(8); PG8_WAIT_L(0); PG8_BAR; PG8_MMA(0, 0, At, B0); PG8_MMA(0, 1, At, B1); PG8_BAR; PG8_SCHED;
;             PG8_LDA(At, 1, 1); PG8_STAGE(PG8_SB(1, 0), b3, voffB); PG8_STAGE(PG8_SB(1, 1), b3 + hstepB, voffB); PG8_STAGE(PG8_SA(1, 0), a3, voffA);
;             PG8_WAIT_V(8); PG8_WAIT_L(0); PG8_BAR; PG8_MMA(1, 0, At, B0); PG8_MMA(1, 1, At, B1); PG8_BAR; PG8_SCHED;
	v_mfma_f32_16x16x32_bf16 v[66:69], v[130:133], v[166:169], v[66:69]
	v_mfma_f32_16x16x32_bf16 v[62:65], v[142:145], v[166:169], v[62:65]
	v_mfma_f32_16x16x32_bf16 v[50:53], v[130:133], v[174:177], v[50:53]
	v_mfma_f32_16x16x32_bf16 v[46:49], v[142:145], v[174:177], v[46:49]
	v_mfma_f32_16x16x32_bf16 v[34:37], v[130:133], v[182:185], v[34:37]
	v_mfma_f32_16x16x32_bf16 v[30:33], v[142:145], v[182:185], v[30:33]
	v_mfma_f32_16x16x32_bf16 v[18:21], v[130:133], v[190:193], v[18:21]
	v_mfma_f32_16x16x32_bf16 v[10:13], v[142:145], v[190:193], v[10:13]
	v_mfma_f32_16x16x32_bf16 v[66:69], v[138:141], v[170:173], v[66:69]
	v_mfma_f32_16x16x32_bf16 v[62:65], v[146:149], v[170:173], v[62:65]
	v_mfma_f32_16x16x32_bf16 v[50:53], v[138:141], v[178:181], v[50:53]
	v_mfma_f32_16x16x32_bf16 v[46:49], v[146:149], v[178:181], v[46:49]
	v_mfma_f32_16x16x32_bf16 v[34:37], v[138:141], v[186:189], v[34:37]
	v_mfma_f32_16x16x32_bf16 v[30:33], v[146:149], v[186:189], v[30:33]
	v_mfma_f32_16x16x32_bf16 v[18:21], v[138:141], v[212:215], v[18:21]
	v_mfma_f32_16x16x32_bf16 v[10:13], v[146:149], v[212:215], v[10:13]
	s_setprio 0
	s_setprio 1
	v_mfma_f32_16x16x32_bf16 v[58:61], v[150:153], v[166:169], v[58:61]
	v_mfma_f32_16x16x32_bf16 v[54:57], v[158:161], v[166:169], v[54:57]
	v_mfma_f32_16x16x32_bf16 v[42:45], v[150:153], v[174:177], v[42:45]
	v_mfma_f32_16x16x32_bf16 v[38:41], v[158:161], v[174:177], v[38:41]
	v_mfma_f32_16x16x32_bf16 v[26:29], v[150:153], v[182:185], v[26:29]
	v_mfma_f32_16x16x32_bf16 v[22:25], v[158:161], v[182:185], v[22:25]
	v_mfma_f32_16x16x32_bf16 v[6:9], v[150:153], v[190:193], v[6:9]
	v_mfma_f32_16x16x32_bf16 v[2:5], v[158:161], v[190:193], v[2:5]
	v_mfma_f32_16x16x32_bf16 v[58:61], v[154:157], v[170:173], v[58:61]
	v_mfma_f32_16x16x32_bf16 v[54:57], v[162:165], v[170:173], v[54:57]
	v_mfma_f32_16x16x32_bf16 v[42:45], v[154:157], v[178:181], v[42:45]
	v_mfma_f32_16x16x32_bf16 v[38:41], v[162:165], v[178:181], v[38:41]
	v_mfma_f32_16x16x32_bf16 v[26:29], v[154:157], v[186:189], v[26:29]
	v_mfma_f32_16x16x32_bf16 v[22:25], v[162:165], v[186:189], v[22:25]
	v_mfma_f32_16x16x32_bf16 v[6:9], v[154:157], v[212:215], v[6:9]
	v_mfma_f32_16x16x32_bf16 v[2:5], v[162:165], v[212:215], v[2:5]
	s_barrier
	s_setprio 0
	s_add_i32 s59, 0, 0x18000
	s_add_i32 s60, 0, 0x1c000
	v_add_u32_e32 v146, s59, v228
	v_add_u32_e32 v162, s60, v228
	ds_read_b128 v[130:133], v146
	ds_read_b128 v[138:141], v146 offset:1024
	ds_read_b128 v[142:145], v146 offset:2048
	ds_read_b128 v[146:149], v146 offset:3072
	ds_read_b128 v[150:153], v162
	ds_read_b128 v[154:157], v162 offset:1024
	ds_read_b128 v[158:161], v162 offset:2048
	ds_read_b128 v[162:165], v162 offset:3072
	s_add_u32 s50, s50, 0x40000
	s_addc_u32 s51, s51, 0
	s_mov_b32 m0, s36
	v_lshl_add_u64 v[224:225], s[50:51], 0, v[196:197]
	ds_read_b128 v[166:169], v244 offset:32768
	ds_read_b128 v[170:173], v244 offset:33792
	ds_read_b128 v[174:177], v244 offset:34816
	ds_read_b128 v[178:181], v244 offset:35840
	ds_read_b128 v[182:185], v244 offset:36864
	ds_read_b128 v[186:189], v244 offset:37888
	ds_read_b128 v[190:193], v244 offset:38912
	ds_read_b128 v[212:215], v244 offset:39936
	global_load_lds_dwordx4 v[224:225], off
	v_lshl_add_u64 v[224:225], s[50:51], 0, v[194:195]
	s_mov_b32 m0, s38
	s_nop 0
	global_load_lds_dwordx4 v[224:225], off
	s_waitcnt vmcnt(8)
	s_waitcnt lgkmcnt(0)
	s_setprio 1
	s_barrier
	v_mfma_f32_16x16x32_bf16 v[134:137], v[130:133], v[166:169], v[134:137]
	v_mfma_f32_16x16x32_bf16 v[126:129], v[142:145], v[166:169], v[126:129]
	v_mfma_f32_16x16x32_bf16 v[114:117], v[130:133], v[174:177], v[114:117]
	v_mfma_f32_16x16x32_bf16 v[110:113], v[142:145], v[174:177], v[110:113]
	v_mfma_f32_16x16x32_bf16 v[98:101], v[130:133], v[182:185], v[98:101]
	v_mfma_f32_16x16x32_bf16 v[94:97], v[142:145], v[182:185], v[94:97]
	v_mfma_f32_16x16x32_bf16 v[82:85], v[130:133], v[190:193], v[82:85]
	v_mfma_f32_16x16x32_bf16 v[78:81], v[142:145], v[190:193], v[78:81]
	v_mfma_f32_16x16x32_bf16 v[134:137], v[138:141], v[170:173], v[134:137]
	v_mfma_f32_16x16x32_bf16 v[126:129], v[146:149], v[170:173], v[126:129]
	v_mfma_f32_16x16x32_bf16 v[114:117], v[138:141], v[178:181], v[114:117]
	v_mfma_f32_16x16x32_bf16 v[110:113], v[146:149], v[178:181], v[110:113]
	v_mfma_f32_16x16x32_bf16 v[98:101], v[138:141], v[186:189], v[98:101]
	v_mfma_f32_16x16x32_bf16 v[94:97], v[146:149], v[186:189], v[94:97]
	v_mfma_f32_16x16x32_bf16 v[82:85], v[138:141], v[212:215], v[82:85]
	v_mfma_f32_16x16x32_bf16 v[78:81], v[146:149], v[212:215], v[78:81]
	s_setprio 0
	s_setprio 1
	v_mfma_f32_16x16x32_bf16 v[122:125], v[150:153], v[166:169], v[122:125]
	v_mfma_f32_16x16x32_bf16 v[118:121], v[158:161], v[166:169], v[118:121]
	v_mfma_f32_16x16x32_bf16 v[106:109], v[150:153], v[174:177], v[106:109]
	v_mfma_f32_16x16x32_bf16 v[102:105], v[158:161], v[174:177], v[102:105]
	v_mfma_f32_16x16x32_bf16 v[90:93], v[150:153], v[182:185], v[90:93]
	v_mfma_f32_16x16x32_bf16 v[86:89], v[158:161], v[182:185], v[86:89]
	v_mfma_f32_16x16x32_bf16 v[74:77], v[150:153], v[190:193], v[74:77]
	v_mfma_f32_16x16x32_bf16 v[70:73], v[158:161], v[190:193], v[70:73]
	v_mfma_f32_16x16x32_bf16 v[122:125], v[154:157], v[170:173], v[122:125]
	v_mfma_f32_16x16x32_bf16 v[118:121], v[162:165], v[170:173], v[118:121]
	v_mfma_f32_16x16x32_bf16 v[106:109], v[154:157], v[178:181], v[106:109]
	v_mfma_f32_16x16x32_bf16 v[102:105], v[162:165], v[178:181], v[102:105]
	v_mfma_f32_16x16x32_bf16 v[90:93], v[154:157], v[186:189], v[90:93]
	v_mfma_f32_16x16x32_bf16 v[86:89], v[162:165], v[186:189], v[86:89]
	v_mfma_f32_16x16x32_bf16 v[74:77], v[154:157], v[212:215], v[74:77]
	v_mfma_f32_16x16x32_bf16 v[70:73], v[162:165], v[212:215], v[70:73]
	s_barrier
; #define PG8_STAGE(bufoff, gbase, voff) do { _Pragma("unroll") for (int _i = 0; _i < 2; ++_i) \
;         __builtin_amdgcn_global_load_lds((const unsigned*)((const char*)(gbase) + (voff)[_i]), (LAS unsigned*)(lds + (bufoff) + ldsw + _i * 8192), 16, 0, 0); } while (0)
; #define PG8_LDA(dst, b, h) do { _Pragma("unroll") for (int m = 0; m < 4; ++m) _Pragma("unroll") for (int k = 0; k < 2; ++k) dst[m][k] = *(const LAS bf16x8*)(lds + PG8_SA(b, h) + aoff + m * 2048 + k * 1024); } while (0)
; #define PG8_LDB(dst, b, h) do { _Pragma("unroll") for (int n = 0; n < 2; ++n) _Pragma("unroll") for (int k = 0; k < 2; ++k) dst[n][k] = *(const LAS bf16x8*)(lds + PG8_SB(b, h) + boff + n * 2048 + k * 1024); } while (0)
; #define PG8_MMA(ai, bj, At, Bt) do { __builtin_amdgcn_s_setprio(1); _Pragma("unroll") for (int m = 0; m < 4; ++m) _Pragma("unroll") for (int n = 0; n < 2; ++n) _Pragma("unroll") for (int k = 0; k < 2; ++k) \
;         acc[ai][bj][m][n] = __builtin_amdgcn_mfma_f32_16x16x32_bf16(Bt[n][k], At[m][k], acc[ai][bj][m][n], 0, 0, 0); __builtin_amdgcn_s_setprio(0); } while (0)
; #define PG8_WAIT_V(n) asm volatile("s_waitcnt vmcnt(" #n ")" ::: "memory")
; #define PG8_WAIT_L(n) asm volatile("s_waitcnt lgkmcnt(" #n ")" ::: "memory")
; #define PG8_BAR __builtin_amdgcn_s_barrier()
; #define PG8_SCHED __builtin_amdgcn_sched_barrier(0)
; template <class Epi, bool SEG>
; __device__ __forceinline__ void gemm_phase(LAS unsigned char* lds, const Gemm g, const int G, const int cidx, const Epi& E) {
;     ...
;             PG8_LDB(B0, 1, 0); PG8_LDB(B1, 1, 1); PG8_SCHED; PG8_LDA(At, 1, 0); PG8_STAGE(PG8_SA(0, 1), a2 + hstepA, voffA);
;             PG8_WAIT_V(8); PG8_WAIT_L(0); PG8_BAR; PG8_MMA(0, 0, At, B0); PG8_MMA(0, 1, At, B1); PG8_BAR; PG8_SCHED;
;             PG8_LDA(At, 1, 1); PG8_STAGE(PG8_SB(1, 0), b3, voffB); PG8_STAGE(PG8_SB(1, 1), b3 + hstepB, voffB); PG8_STAGE(PG8_SA(1, 0), a3, voffA);
;             PG8_WAIT_V(8); PG8_WAIT_L(0); PG8_BAR; PG8_MMA(1, 0, At, B0); PG8_MMA(1, 1, At, B1); PG8_BAR; PG8_SCHED;
;         }
;         if (wr == 0) PG8_BAR;
	s_setprio 0
	s_add_i32 s50, s59, s9
	v_lshl_add_u64 v[216:217], v[216:217], 0, s[28:29]
	s_mov_b32 m0, s50
	ds_read_b128 v[166:169], v244 offset:49152
	ds_read_b128 v[170:173], v244 offset:50176
	ds_read_b128 v[174:177], v244 offset:51200
	ds_read_b128 v[178:181], v244 offset:52224
	ds_read_b128 v[182:185], v244 offset:53248
	ds_read_b128 v[186:189], v244 offset:54272
	ds_read_b128 v[190:193], v244 offset:55296
	ds_read_b128 v[212:215], v244 offset:56320
	global_load_lds_dwordx4 v[216:217], off
	s_add_i32 m0, s50, 0x2000
	s_add_u32 s48, s48, 0x40080
	v_lshl_add_u64 v[216:217], v[218:219], 0, s[28:29]
	s_addc_u32 s49, s49, 0
	s_add_i32 s50, s60, s9
	global_load_lds_dwordx4 v[216:217], off
	v_lshl_add_u64 v[216:217], s[48:49], 0, v[0:1]
	s_mov_b32 m0, s50
	s_nop 0
	global_load_lds_dwordx4 v[216:217], off
	v_lshl_add_u64 v[216:217], s[48:49], 0, v[14:15]
	s_add_i32 m0, s50, 0x2000
	s_nop 0
	global_load_lds_dwordx4 v[216:217], off
	v_lshl_add_u64 v[216:217], v[220:221], 0, s[28:29]
	s_mov_b32 m0, s39
	s_nop 0
	global_load_lds_dwordx4 v[216:217], off
	v_lshl_add_u64 v[216:217], v[222:223], 0, s[28:29]
	s_mov_b32 m0, s52
	s_nop 0
	global_load_lds_dwordx4 v[216:217], off
	s_waitcnt vmcnt(8)
	s_waitcnt lgkmcnt(0)
	s_setprio 1
	s_barrier
	v_mfma_f32_16x16x32_bf16 v[66:69], v[130:133], v[166:169], v[66:69]
	v_mfma_f32_16x16x32_bf16 v[62:65], v[142:145], v[166:169], v[62:65]
	v_mfma_f32_16x16x32_bf16 v[50:53], v[130:133], v[174:177], v[50:53]
	v_mfma_f32_16x16x32_bf16 v[46:49], v[142:145], v[174:177], v[46:49]
	v_mfma_f32_16x16x32_bf16 v[34:37], v[130:133], v[182:185], v[34:37]
	v_mfma_f32_16x16x32_bf16 v[30:33], v[142:145], v[182:185], v[30:33]
	v_mfma_f32_16x16x32_bf16 v[18:21], v[130:133], v[190:193], v[18:21]
	v_mfma_f32_16x16x32_bf16 v[10:13], v[142:145], v[190:193], v[10:13]
	v_mfma_f32_16x16x32_bf16 v[66:69], v[138:141], v[170:173], v[66:69]
	v_mfma_f32_16x16x32_bf16 v[62:65], v[146:149], v[170:173], v[62:65]
	v_mfma_f32_16x16x32_bf16 v[50:53], v[138:141], v[178:181], v[50:53]
	v_mfma_f32_16x16x32_bf16 v[46:49], v[146:149], v[178:181], v[46:49]
	v_mfma_f32_16x16x32_bf16 v[34:37], v[138:141], v[186:189], v[34:37]
	v_mfma_f32_16x16x32_bf16 v[30:33], v[146:149], v[186:189], v[30:33]
	v_mfma_f32_16x16x32_bf16 v[18:21], v[138:141], v[212:215], v[18:21]
	v_mfma_f32_16x16x32_bf16 v[10:13], v[146:149], v[212:215], v[10:13]
	s_setprio 0
	s_setprio 1
	v_mfma_f32_16x16x32_bf16 v[58:61], v[150:153], v[166:169], v[58:61]
	v_mfma_f32_16x16x32_bf16 v[54:57], v[158:161], v[166:169], v[54:57]
	v_mfma_f32_16x16x32_bf16 v[42:45], v[150:153], v[174:177], v[42:45]
	v_mfma_f32_16x16x32_bf16 v[38:41], v[158:161], v[174:177], v[38:41]
	v_mfma_f32_16x16x32_bf16 v[26:29], v[150:153], v[182:185], v[26:29]
	v_mfma_f32_16x16x32_bf16 v[22:25], v[158:161], v[182:185], v[22:25]
	v_mfma_f32_16x16x32_bf16 v[6:9], v[150:153], v[190:193], v[6:9]
	v_mfma_f32_16x16x32_bf16 v[2:5], v[158:161], v[190:193], v[2:5]
	v_mfma_f32_16x16x32_bf16 v[58:61], v[154:157], v[170:173], v[58:61]
	v_mfma_f32_16x16x32_bf16 v[54:57], v[162:165], v[170:173], v[54:57]
	v_mfma_f32_16x16x32_bf16 v[42:45], v[154:157], v[178:181], v[42:45]
	v_mfma_f32_16x16x32_bf16 v[38:41], v[162:165], v[178:181], v[38:41]
	v_mfma_f32_16x16x32_bf16 v[26:29], v[154:157], v[186:189], v[26:29]
	v_mfma_f32_16x16x32_bf16 v[22:25], v[162:165], v[186:189], v[22:25]
	v_mfma_f32_16x16x32_bf16 v[6:9], v[154:157], v[212:215], v[6:9]
	v_mfma_f32_16x16x32_bf16 v[2:5], v[162:165], v[212:215], v[2:5]
	s_barrier
	s_setprio 0
	s_add_i32 s58, s58, 2
	s_add_u32 s40, s40, 0x100
	s_addc_u32 s41, s41, 0
	s_add_u32 s56, s56, 0x100
	s_addc_u32 s57, s57, 0
	s_cmp_gt_u32 s58, 13
	s_cbranch_scc0 .LBB0_706
	s_and_b64 vcc, exec, s[12:13]
	s_cbranch_vccz .LBB0_709
	s_barrier

; #define PG8_STAGE(bufoff, gbase, voff) do { _Pragma("unroll") for (int _i = 0; _i < 2; ++_i) \
;         __builtin_amdgcn_global_load_lds((const unsigned*)((const char*)(gbase) + (voff)[_i]), (LAS unsigned*)(lds + (bufoff) + ldsw + _i * 8192), 16, 0, 0); } while (0)
; #define PG8_LDA(dst, b, h) do { _Pragma("unroll") for (int m = 0; m < 4; ++m) _Pragma("unroll") for (int k = 0; k < 2; ++k) dst[m][k] = *(const LAS bf16x8*)(lds + PG8_SA(b, h) + aoff + m * 2048 + k * 1024); } while (0)
; #define PG8_LDB(dst, b, h) do { _Pragma("unroll") for (int n = 0; n < 2; ++n) _Pragma("unroll") for (int k = 0; k < 2; ++k) dst[n][k] = *(const LAS bf16x8*)(lds + PG8_SB(b, h) + boff + n * 2048 + k * 1024); } while (0)
; #define PG8_WAIT_V(n) asm volatile("s_waitcnt vmcnt(" #n ")" ::: "memory")
; #define PG8_BAR __builtin_amdgcn_s_barrier()
; template <class Epi, bool SEG>
; __device__ __forceinline__ void gemm_phase(LAS unsigned char* lds, const Gemm g, const int G, const int cidx, const Epi& E) {
;     ...
;         for (int t = 0; t < nt; t += 2) {
;             const bool last = (t == nt - 2);
;             const char* a1 = cA + (size_t)(t + 1) * kstep;
;             const char* a2 = last ? nA : cA + (size_t)(t + 2) * kstep; const char* b2 = last ? nB : cB + (size_t)(t + 2) * kstep;
;             const char* a3 = a2 + kstep; const char* b3 = b2 + kstep;
;             PG8_LDB(B0, 0, 0); PG8_LDB(B1, 0, 1); PG8_SCHED; PG8_LDA(At, 0, 0); PG8_STAGE(PG8_SA(1, 1), a1 + hstepA, voffA);
;             PG8_WAIT_V(8); PG8_WAIT_L(0); PG8_BAR; PG8_MMA(0, 0, At, B0); PG8_MMA(0, 1, At, B1); PG8_BAR; PG8_SCHED;
;             PG8_LDA(At, 0, 1); PG8_STAGE(PG8_SB(0, 0), b2, voffB); PG8_STAGE(PG8_SB(0, 1), b2 + hstepB, voffB); PG8_STAGE(PG8_SA(0, 0), a2, voffA);
;             PG8_WAIT_V(8); PG8_WAIT_L(0); PG8_BAR; PG8_MMA(1, 0, At, B0); PG8_MMA(1, 1, At, B1); PG8_BAR; PG8_SCHED;
;             PG8_LDB(B0, 1, 0); PG8_LDB(B1, 1, 1); PG8_SCHED; PG8_LDA(At, 1, 0); PG8_STAGE(PG8_SA(0, 1), a2 + hstepA, voffA);
;             PG8_WAIT_V(8); PG8_WAIT_L(0); PG8_BAR; PG8_MMA(0, 0, At, B0); PG8_MMA(0, 1, At, B1); PG8_BAR; PG8_SCHED;
;             PG8_LDA(At, 1, 1); PG8_STAGE(PG8_SB(1, 0), b3, voffB); PG8_STAGE(PG8_SB(1, 1), b3 + hstepB, voffB); PG8_STAGE(PG8_SA(1, 0), a3, voffA);
;             PG8_WAIT_V(8); PG8_WAIT_L(0); PG8_BAR; PG8_MMA(1, 0, At, B0); PG8_MMA(1, 1, At, B1); PG8_BAR; PG8_SCHED;
.LBB0_786:
	s_add_u32 s22, s6, 0xfffc2080
	s_addc_u32 s23, s7, -1
	s_add_i32 s55, 0, 0x10000
	s_cmp_eq_u32 s54, 12
	s_cselect_b32 s41, s17, s23
	s_cselect_b32 s40, s16, s22
	s_cselect_b32 s23, s15, s53
	s_cselect_b32 s22, s21, s52
	s_add_i32 s58, 0, 0x14000
	v_add_u32_e32 v114, s55, v243
	v_add_u32_e32 v130, s58, v243
	ds_read_b128 v[102:105], v114
	ds_read_b128 v[106:109], v114 offset:1024
	ds_read_b128 v[110:113], v114 offset:2048
	ds_read_b128 v[114:117], v114 offset:3072
	ds_read_b128 v[118:121], v130
	ds_read_b128 v[122:125], v130 offset:1024
	ds_read_b128 v[126:129], v130 offset:2048
	ds_read_b128 v[130:133], v130 offset:3072
	v_lshl_add_u64 v[208:209], s[6:7], 0, v[198:199]
	s_add_i32 m0, s11, 0xc000
	ds_read_b128 v[166:169], v247
	ds_read_b128 v[170:173], v247 offset:1024
	ds_read_b128 v[174:177], v247 offset:2048
	ds_read_b128 v[178:181], v247 offset:3072
	ds_read_b128 v[182:185], v247 offset:4096
	ds_read_b128 v[186:189], v247 offset:5120
	ds_read_b128 v[212:215], v247 offset:6144
	ds_read_b128 v[216:219], v247 offset:7168
	global_load_lds_dwordx4 v[208:209], off
	v_lshl_add_u64 v[208:209], s[6:7], 0, v[200:201]
	s_add_i32 m0, s11, 0xe000
	s_nop 0
	global_load_lds_dwordx4 v[208:209], off
	s_waitcnt vmcnt(8)
	s_waitcnt lgkmcnt(0)
	s_setprio 1
	s_barrier
	v_mfma_f32_16x16x32_bf16 v[162:165], v[102:105], v[166:169], v[162:165]
	v_mfma_f32_16x16x32_bf16 v[66:69], v[110:113], v[166:169], v[66:69]
	v_mfma_f32_16x16x32_bf16 v[158:161], v[102:105], v[174:177], v[158:161]
	v_mfma_f32_16x16x32_bf16 v[62:65], v[110:113], v[174:177], v[62:65]
	v_mfma_f32_16x16x32_bf16 v[146:149], v[102:105], v[182:185], v[146:149]
	v_mfma_f32_16x16x32_bf16 v[50:53], v[110:113], v[182:185], v[50:53]
	v_mfma_f32_16x16x32_bf16 v[138:141], v[102:105], v[212:215], v[138:141]
	v_mfma_f32_16x16x32_bf16 v[42:45], v[110:113], v[212:215], v[42:45]
	v_mfma_f32_16x16x32_bf16 v[162:165], v[106:109], v[170:173], v[162:165]
	v_mfma_f32_16x16x32_bf16 v[66:69], v[114:117], v[170:173], v[66:69]
	v_mfma_f32_16x16x32_bf16 v[158:161], v[106:109], v[178:181], v[158:161]
	v_mfma_f32_16x16x32_bf16 v[62:65], v[114:117], v[178:181], v[62:65]
	v_mfma_f32_16x16x32_bf16 v[146:149], v[106:109], v[186:189], v[146:149]
	v_mfma_f32_16x16x32_bf16 v[50:53], v[114:117], v[186:189], v[50:53]
	v_mfma_f32_16x16x32_bf16 v[138:141], v[106:109], v[216:219], v[138:141]
	v_mfma_f32_16x16x32_bf16 v[42:45], v[114:117], v[216:219], v[42:45]
	s_setprio 0
	s_setprio 1
	v_mfma_f32_16x16x32_bf16 v[154:157], v[118:121], v[166:169], v[154:157]
	v_mfma_f32_16x16x32_bf16 v[58:61], v[126:129], v[166:169], v[58:61]
	v_mfma_f32_16x16x32_bf16 v[150:153], v[118:121], v[174:177], v[150:153]
	v_mfma_f32_16x16x32_bf16 v[54:57], v[126:129], v[174:177], v[54:57]
	v_mfma_f32_16x16x32_bf16 v[142:145], v[118:121], v[182:185], v[142:145]
	v_mfma_f32_16x16x32_bf16 v[46:49], v[126:129], v[182:185], v[46:49]
	v_mfma_f32_16x16x32_bf16 v[134:137], v[118:121], v[212:215], v[134:137]
	v_mfma_f32_16x16x32_bf16 v[38:41], v[126:129], v[212:215], v[38:41]
	v_mfma_f32_16x16x32_bf16 v[154:157], v[122:125], v[170:173], v[154:157]
	v_mfma_f32_16x16x32_bf16 v[58:61], v[130:133], v[170:173], v[58:61]
	v_mfma_f32_16x16x32_bf16 v[150:153], v[122:125], v[178:181], v[150:153]
	v_mfma_f32_16x16x32_bf16 v[54:57], v[130:133], v[178:181], v[54:57]
	v_mfma_f32_16x16x32_bf16 v[142:145], v[122:125], v[186:189], v[142:145]
	v_mfma_f32_16x16x32_bf16 v[46:49], v[130:133], v[186:189], v[46:49]
	v_mfma_f32_16x16x32_bf16 v[134:137], v[122:125], v[216:219], v[134:137]
	v_mfma_f32_16x16x32_bf16 v[38:41], v[130:133], v[216:219], v[38:41]
	s_barrier
	s_setprio 0
	s_add_i32 s55, s55, s10
	v_lshl_add_u64 v[208:209], s[22:23], 0, v[0:1]
	s_mov_b32 m0, s55
	ds_read_b128 v[166:169], v247 offset:16384
	ds_read_b128 v[170:173], v247 offset:17408
	ds_read_b128 v[174:177], v247 offset:18432
	ds_read_b128 v[178:181], v247 offset:19456
	ds_read_b128 v[182:185], v247 offset:20480
	ds_read_b128 v[186:189], v247 offset:21504
	ds_read_b128 v[212:215], v247 offset:22528
	ds_read_b128 v[216:219], v247 offset:23552
	global_load_lds_dwordx4 v[208:209], off
	s_add_i32 m0, s55, 0x2000
	s_add_u32 s56, s22, 0x40000
	v_lshl_add_u64 v[220:221], s[22:23], 0, v[192:193]
	s_addc_u32 s57, s23, 0
	s_add_i32 s55, s58, s10
	global_load_lds_dwordx4 v[220:221], off
	v_lshl_add_u64 v[222:223], s[56:57], 0, v[0:1]
	s_mov_b32 m0, s55
	v_lshl_add_u64 v[224:225], s[40:41], 0, v[190:191]
	global_load_lds_dwordx4 v[222:223], off
	v_lshl_add_u64 v[222:223], s[56:57], 0, v[192:193]
	s_add_i32 m0, s55, 0x2000
	s_nop 0
	global_load_lds_dwordx4 v[222:223], off
	v_lshl_add_u64 v[222:223], s[40:41], 0, v[14:15]
	s_mov_b32 m0, s11
	s_nop 0
	global_load_lds_dwordx4 v[222:223], off
	s_mov_b32 m0, s9
	s_nop 0
	global_load_lds_dwordx4 v[224:225], off
	s_waitcnt vmcnt(8)
	s_waitcnt lgkmcnt(0)
	s_setprio 1
	s_barrier
; #define PG8_STAGE(bufoff, gbase, voff) do { _Pragma("unroll") for (int _i = 0; _i < 2; ++_i) \
;         __builtin_amdgcn_global_load_lds((const unsigned*)((const char*)(gbase) + (voff)[_i]), (LAS unsigned*)(lds + (bufoff) + ldsw + _i * 8192), 16, 0, 0); } while (0)
; #define PG8_LDA(dst, b, h) do { _Pragma("unroll") for (int m = 0; m < 4; ++m) _Pragma("unroll") for (int k = 0; k < 2; ++k) dst[m][k] = *(const LAS bf16x8*)(lds + PG8_SA(b, h) + aoff + m * 2048 + k * 1024); } while (0)
; #define PG8_LDB(dst, b, h) do { _Pragma("unroll") for (int n = 0; n < 2; ++n) _Pragma("unroll") for (int k = 0; k < 2; ++k) dst[n][k] = *(const LAS bf16x8*)(lds + PG8_SB(b, h) + boff + n * 2048 + k * 1024); } while (0)
; #define PG8_MMA(ai, bj, At, Bt) do { __builtin_amdgcn_s_setprio(1); _Pragma("unroll") for (int m = 0; m < 4; ++m) _Pragma("unroll") for (int n = 0; n < 2; ++n) _Pragma("unroll") for (int k = 0; k < 2; ++k) \
;         acc[ai][bj][m][n] = __builtin_amdgcn_mfma_f32_16x16x32_bf16(Bt[n][k], At[m][k], acc[ai][bj][m][n], 0, 0, 0); __builtin_amdgcn_s_setprio(0); } while (0)
; #define PG8_WAIT_V(n) asm volatile("s_waitcnt vmcnt(" #n ")" ::: "memory")
; #define PG8_WAIT_L(n) asm volatile("s_waitcnt lgkmcnt(" #n ")" ::: "memory")
; #define PG8_BAR __builtin_amdgcn_s_barrier()
; #define PG8_SCHED __builtin_amdgcn_sched_barrier(0)
; template <class Epi, bool SEG>
; __device__ __forceinline__ void gemm_phase(LAS unsigned char* lds, const Gemm g, const int G, const int cidx, const Epi& E) {
;     ...
;             PG8_LDA(At, 0, 1); PG8_STAGE(PG8_SB(0, 0), b2, voffB); PG8_STAGE(PG8_SB(0, 1), b2 + hstepB, voffB); PG8_STAGE(PG8_SA(0, 0), a2, voffA);
;             PG8_WAIT_V(8); PG8_WAIT_L(0); PG8_BAR; PG8_MMA(1, 0, At, B0); PG8_MMA(1, 1, At, B1); PG8_BAR; PG8_SCHED;
;             PG8_LDB(B0, 1, 0); PG8_LDB(B1, 1, 1); PG8_SCHED; PG8_LDA(At, 1, 0); PG8_STAGE(PG8_SA(0, 1), a2 + hstepA, voffA);
;             PG8_WAIT_V(8); PG8_WAIT_L(0); PG8_BAR; PG8_MMA(0, 0, At, B0); PG8_MMA(0, 1, At, B1); PG8_BAR; PG8_SCHED;
;             PG8_LDA(At, 1, 1); PG8_STAGE(PG8_SB(1, 0), b3, voffB); PG8_STAGE(PG8_SB(1, 1), b3 + hstepB, voffB); PG8_STAGE(PG8_SA(1, 0), a3, voffA);
;             PG8_WAIT_V(8); PG8_WAIT_L(0); PG8_BAR; PG8_MMA(1, 0, At, B0); PG8_MMA(1, 1, At, B1); PG8_BAR; PG8_SCHED;
	v_mfma_f32_16x16x32_bf16 v[98:101], v[102:105], v[166:169], v[98:101]
	v_mfma_f32_16x16x32_bf16 v[34:37], v[110:113], v[166:169], v[34:37]
	v_mfma_f32_16x16x32_bf16 v[94:97], v[102:105], v[174:177], v[94:97]
	v_mfma_f32_16x16x32_bf16 v[30:33], v[110:113], v[174:177], v[30:33]
	v_mfma_f32_16x16x32_bf16 v[82:85], v[102:105], v[182:185], v[82:85]
	v_mfma_f32_16x16x32_bf16 v[18:21], v[110:113], v[182:185], v[18:21]
	v_mfma_f32_16x16x32_bf16 v[74:77], v[102:105], v[212:215], v[74:77]
	v_mfma_f32_16x16x32_bf16 v[6:9], v[110:113], v[212:215], v[6:9]
	v_mfma_f32_16x16x32_bf16 v[98:101], v[106:109], v[170:173], v[98:101]
	v_mfma_f32_16x16x32_bf16 v[34:37], v[114:117], v[170:173], v[34:37]
	v_mfma_f32_16x16x32_bf16 v[94:97], v[106:109], v[178:181], v[94:97]
	v_mfma_f32_16x16x32_bf16 v[30:33], v[114:117], v[178:181], v[30:33]
	v_mfma_f32_16x16x32_bf16 v[82:85], v[106:109], v[186:189], v[82:85]
	v_mfma_f32_16x16x32_bf16 v[18:21], v[114:117], v[186:189], v[18:21]
	v_mfma_f32_16x16x32_bf16 v[74:77], v[106:109], v[216:219], v[74:77]
	v_mfma_f32_16x16x32_bf16 v[6:9], v[114:117], v[216:219], v[6:9]
	s_setprio 0
	s_setprio 1
	v_mfma_f32_16x16x32_bf16 v[90:93], v[118:121], v[166:169], v[90:93]
	v_mfma_f32_16x16x32_bf16 v[26:29], v[126:129], v[166:169], v[26:29]
	v_mfma_f32_16x16x32_bf16 v[86:89], v[118:121], v[174:177], v[86:89]
	v_mfma_f32_16x16x32_bf16 v[22:25], v[126:129], v[174:177], v[22:25]
	v_mfma_f32_16x16x32_bf16 v[78:81], v[118:121], v[182:185], v[78:81]
	v_mfma_f32_16x16x32_bf16 v[10:13], v[126:129], v[182:185], v[10:13]
	v_mfma_f32_16x16x32_bf16 v[70:73], v[118:121], v[212:215], v[70:73]
	v_mfma_f32_16x16x32_bf16 v[2:5], v[126:129], v[212:215], v[2:5]
	v_mfma_f32_16x16x32_bf16 v[90:93], v[122:125], v[170:173], v[90:93]
	v_mfma_f32_16x16x32_bf16 v[26:29], v[130:133], v[170:173], v[26:29]
	v_mfma_f32_16x16x32_bf16 v[86:89], v[122:125], v[178:181], v[86:89]
	v_mfma_f32_16x16x32_bf16 v[22:25], v[130:133], v[178:181], v[22:25]
	v_mfma_f32_16x16x32_bf16 v[78:81], v[122:125], v[186:189], v[78:81]
	v_mfma_f32_16x16x32_bf16 v[10:13], v[130:133], v[186:189], v[10:13]
	v_mfma_f32_16x16x32_bf16 v[70:73], v[122:125], v[216:219], v[70:73]
	v_mfma_f32_16x16x32_bf16 v[2:5], v[130:133], v[216:219], v[2:5]
	s_barrier
	s_setprio 0
	s_add_i32 s55, 0, 0x18000
	s_add_i32 s56, 0, 0x1c000
	v_add_u32_e32 v114, s55, v243
	v_add_u32_e32 v130, s56, v243
	ds_read_b128 v[102:105], v114
	ds_read_b128 v[106:109], v114 offset:1024
	ds_read_b128 v[110:113], v114 offset:2048
	ds_read_b128 v[114:117], v114 offset:3072
	ds_read_b128 v[118:121], v130
	ds_read_b128 v[122:125], v130 offset:1024
	ds_read_b128 v[126:129], v130 offset:2048
	ds_read_b128 v[130:133], v130 offset:3072
	s_add_u32 s40, s40, 0x3e000
	s_addc_u32 s41, s41, 0
	s_mov_b32 m0, s36
	v_lshl_add_u64 v[226:227], s[40:41], 0, v[14:15]
	ds_read_b128 v[166:169], v247 offset:32768
	ds_read_b128 v[170:173], v247 offset:33792
	ds_read_b128 v[174:177], v247 offset:34816
	ds_read_b128 v[178:181], v247 offset:35840
	ds_read_b128 v[182:185], v247 offset:36864
	ds_read_b128 v[186:189], v247 offset:37888
	ds_read_b128 v[212:215], v247 offset:38912
	ds_read_b128 v[216:219], v247 offset:39936
	global_load_lds_dwordx4 v[226:227], off
	v_lshl_add_u64 v[226:227], s[40:41], 0, v[190:191]
	s_mov_b32 m0, s12
	s_nop 0
	global_load_lds_dwordx4 v[226:227], off
	s_waitcnt vmcnt(8)
	s_waitcnt lgkmcnt(0)
	s_setprio 1
	s_barrier
	v_mfma_f32_16x16x32_bf16 v[162:165], v[102:105], v[166:169], v[162:165]
	v_mfma_f32_16x16x32_bf16 v[66:69], v[110:113], v[166:169], v[66:69]
	v_mfma_f32_16x16x32_bf16 v[158:161], v[102:105], v[174:177], v[158:161]
	v_mfma_f32_16x16x32_bf16 v[62:65], v[110:113], v[174:177], v[62:65]
	v_mfma_f32_16x16x32_bf16 v[146:149], v[102:105], v[182:185], v[146:149]
	v_mfma_f32_16x16x32_bf16 v[50:53], v[110:113], v[182:185], v[50:53]
	v_mfma_f32_16x16x32_bf16 v[138:141], v[102:105], v[212:215], v[138:141]
	v_mfma_f32_16x16x32_bf16 v[42:45], v[110:113], v[212:215], v[42:45]
	v_mfma_f32_16x16x32_bf16 v[162:165], v[106:109], v[170:173], v[162:165]
	v_mfma_f32_16x16x32_bf16 v[66:69], v[114:117], v[170:173], v[66:69]
	v_mfma_f32_16x16x32_bf16 v[158:161], v[106:109], v[178:181], v[158:161]
	v_mfma_f32_16x16x32_bf16 v[62:65], v[114:117], v[178:181], v[62:65]
	v_mfma_f32_16x16x32_bf16 v[146:149], v[106:109], v[186:189], v[146:149]
	v_mfma_f32_16x16x32_bf16 v[50:53], v[114:117], v[186:189], v[50:53]
	v_mfma_f32_16x16x32_bf16 v[138:141], v[106:109], v[216:219], v[138:141]
	v_mfma_f32_16x16x32_bf16 v[42:45], v[114:117], v[216:219], v[42:45]
	s_setprio 0
	s_setprio 1
	v_mfma_f32_16x16x32_bf16 v[154:157], v[118:121], v[166:169], v[154:157]
	v_mfma_f32_16x16x32_bf16 v[58:61], v[126:129], v[166:169], v[58:61]
	v_mfma_f32_16x16x32_bf16 v[150:153], v[118:121], v[174:177], v[150:153]
	v_mfma_f32_16x16x32_bf16 v[54:57], v[126:129], v[174:177], v[54:57]
	v_mfma_f32_16x16x32_bf16 v[142:145], v[118:121], v[182:185], v[142:145]
	v_mfma_f32_16x16x32_bf16 v[46:49], v[126:129], v[182:185], v[46:49]
	v_mfma_f32_16x16x32_bf16 v[134:137], v[118:121], v[212:215], v[134:137]
	v_mfma_f32_16x16x32_bf16 v[38:41], v[126:129], v[212:215], v[38:41]
	v_mfma_f32_16x16x32_bf16 v[154:157], v[122:125], v[170:173], v[154:157]
	v_mfma_f32_16x16x32_bf16 v[58:61], v[130:133], v[170:173], v[58:61]
	v_mfma_f32_16x16x32_bf16 v[150:153], v[122:125], v[178:181], v[150:153]
	v_mfma_f32_16x16x32_bf16 v[54:57], v[130:133], v[178:181], v[54:57]
	v_mfma_f32_16x16x32_bf16 v[142:145], v[122:125], v[186:189], v[142:145]
	v_mfma_f32_16x16x32_bf16 v[46:49], v[130:133], v[186:189], v[46:49]
	v_mfma_f32_16x16x32_bf16 v[134:137], v[122:125], v[216:219], v[134:137]
	v_mfma_f32_16x16x32_bf16 v[38:41], v[130:133], v[216:219], v[38:41]
	s_barrier
; #define PG8_STAGE(bufoff, gbase, voff) do { _Pragma("unroll") for (int _i = 0; _i < 2; ++_i) \
;         __builtin_amdgcn_global_load_lds((const unsigned*)((const char*)(gbase) + (voff)[_i]), (LAS unsigned*)(lds + (bufoff) + ldsw + _i * 8192), 16, 0, 0); } while (0)
; #define PG8_LDA(dst, b, h) do { _Pragma("unroll") for (int m = 0; m < 4; ++m) _Pragma("unroll") for (int k = 0; k < 2; ++k) dst[m][k] = *(const LAS bf16x8*)(lds + PG8_SA(b, h) + aoff + m * 2048 + k * 1024); } while (0)
; #define PG8_LDB(dst, b, h) do { _Pragma("unroll") for (int n = 0; n < 2; ++n) _Pragma("unroll") for (int k = 0; k < 2; ++k) dst[n][k] = *(const LAS bf16x8*)(lds + PG8_SB(b, h) + boff + n * 2048 + k * 1024); } while (0)
; #define PG8_MMA(ai, bj, At, Bt) do { __builtin_amdgcn_s_setprio(1); _Pragma("unroll") for (int m = 0; m < 4; ++m) _Pragma("unroll") for (int n = 0; n < 2; ++n) _Pragma("unroll") for (int k = 0; k < 2; ++k) \
;         acc[ai][bj][m][n] = __builtin_amdgcn_mfma_f32_16x16x32_bf16(Bt[n][k], At[m][k], acc[ai][bj][m][n], 0, 0, 0); __builtin_amdgcn_s_setprio(0); } while (0)
; #define PG8_WAIT_V(n) asm volatile("s_waitcnt vmcnt(" #n ")" ::: "memory")
; #define PG8_WAIT_L(n) asm volatile("s_waitcnt lgkmcnt(" #n ")" ::: "memory")
; #define PG8_BAR __builtin_amdgcn_s_barrier()
; #define PG8_SCHED __builtin_amdgcn_sched_barrier(0)
; template <class Epi, bool SEG>
; __device__ __forceinline__ void gemm_phase(LAS unsigned char* lds, const Gemm g, const int G, const int cidx, const Epi& E) {
;     ...
;             PG8_LDB(B0, 1, 0); PG8_LDB(B1, 1, 1); PG8_SCHED; PG8_LDA(At, 1, 0); PG8_STAGE(PG8_SA(0, 1), a2 + hstepA, voffA);
;             PG8_WAIT_V(8); PG8_WAIT_L(0); PG8_BAR; PG8_MMA(0, 0, At, B0); PG8_MMA(0, 1, At, B1); PG8_BAR; PG8_SCHED;
;             PG8_LDA(At, 1, 1); PG8_STAGE(PG8_SB(1, 0), b3, voffB); PG8_STAGE(PG8_SB(1, 1), b3 + hstepB, voffB); PG8_STAGE(PG8_SA(1, 0), a3, voffA);
;             PG8_WAIT_V(8); PG8_WAIT_L(0); PG8_BAR; PG8_MMA(1, 0, At, B0); PG8_MMA(1, 1, At, B1); PG8_BAR; PG8_SCHED;
;         }
;         if (wr == 0) PG8_BAR;
	s_setprio 0
	s_add_i32 s40, s55, s10
	v_lshl_add_u64 v[208:209], v[208:209], 0, s[28:29]
	s_mov_b32 m0, s40
	ds_read_b128 v[166:169], v247 offset:49152
	ds_read_b128 v[170:173], v247 offset:50176
	ds_read_b128 v[174:177], v247 offset:51200
	ds_read_b128 v[178:181], v247 offset:52224
	ds_read_b128 v[182:185], v247 offset:53248
	ds_read_b128 v[186:189], v247 offset:54272
	ds_read_b128 v[212:215], v247 offset:55296
	ds_read_b128 v[216:219], v247 offset:56320
	global_load_lds_dwordx4 v[208:209], off
	s_add_i32 m0, s40, 0x2000
	s_add_u32 s22, s22, 0x40080
	v_lshl_add_u64 v[208:209], v[220:221], 0, s[28:29]
	s_addc_u32 s23, s23, 0
	s_add_i32 s40, s56, s10
	global_load_lds_dwordx4 v[208:209], off
	v_lshl_add_u64 v[208:209], s[22:23], 0, v[0:1]
	s_mov_b32 m0, s40
	s_nop 0
	global_load_lds_dwordx4 v[208:209], off
	v_lshl_add_u64 v[208:209], s[22:23], 0, v[192:193]
	s_add_i32 m0, s40, 0x2000
	s_nop 0
	global_load_lds_dwordx4 v[208:209], off
	v_lshl_add_u64 v[208:209], v[222:223], 0, s[28:29]
	s_mov_b32 m0, s13
	s_nop 0
	global_load_lds_dwordx4 v[208:209], off
	v_lshl_add_u64 v[208:209], v[224:225], 0, s[28:29]
	s_mov_b32 m0, s8
	s_nop 0
	global_load_lds_dwordx4 v[208:209], off
	s_waitcnt vmcnt(8)
	s_waitcnt lgkmcnt(0)
	s_setprio 1
	s_barrier
	v_mfma_f32_16x16x32_bf16 v[98:101], v[102:105], v[166:169], v[98:101]
	v_mfma_f32_16x16x32_bf16 v[34:37], v[110:113], v[166:169], v[34:37]
	v_mfma_f32_16x16x32_bf16 v[94:97], v[102:105], v[174:177], v[94:97]
	v_mfma_f32_16x16x32_bf16 v[30:33], v[110:113], v[174:177], v[30:33]
	v_mfma_f32_16x16x32_bf16 v[82:85], v[102:105], v[182:185], v[82:85]
	v_mfma_f32_16x16x32_bf16 v[18:21], v[110:113], v[182:185], v[18:21]
	v_mfma_f32_16x16x32_bf16 v[74:77], v[102:105], v[212:215], v[74:77]
	v_mfma_f32_16x16x32_bf16 v[6:9], v[110:113], v[212:215], v[6:9]
	v_mfma_f32_16x16x32_bf16 v[98:101], v[106:109], v[170:173], v[98:101]
	v_mfma_f32_16x16x32_bf16 v[34:37], v[114:117], v[170:173], v[34:37]
	v_mfma_f32_16x16x32_bf16 v[94:97], v[106:109], v[178:181], v[94:97]
	v_mfma_f32_16x16x32_bf16 v[30:33], v[114:117], v[178:181], v[30:33]
	v_mfma_f32_16x16x32_bf16 v[82:85], v[106:109], v[186:189], v[82:85]
	v_mfma_f32_16x16x32_bf16 v[18:21], v[114:117], v[186:189], v[18:21]
	v_mfma_f32_16x16x32_bf16 v[74:77], v[106:109], v[216:219], v[74:77]
	v_mfma_f32_16x16x32_bf16 v[6:9], v[114:117], v[216:219], v[6:9]
	s_setprio 0
	s_setprio 1
	v_mfma_f32_16x16x32_bf16 v[90:93], v[118:121], v[166:169], v[90:93]
	v_mfma_f32_16x16x32_bf16 v[26:29], v[126:129], v[166:169], v[26:29]
	v_mfma_f32_16x16x32_bf16 v[86:89], v[118:121], v[174:177], v[86:89]
	v_mfma_f32_16x16x32_bf16 v[22:25], v[126:129], v[174:177], v[22:25]
	v_mfma_f32_16x16x32_bf16 v[78:81], v[118:121], v[182:185], v[78:81]
	v_mfma_f32_16x16x32_bf16 v[10:13], v[126:129], v[182:185], v[10:13]
	v_mfma_f32_16x16x32_bf16 v[70:73], v[118:121], v[212:215], v[70:73]
	v_mfma_f32_16x16x32_bf16 v[2:5], v[126:129], v[212:215], v[2:5]
	v_mfma_f32_16x16x32_bf16 v[90:93], v[122:125], v[170:173], v[90:93]
	v_mfma_f32_16x16x32_bf16 v[26:29], v[130:133], v[170:173], v[26:29]
	v_mfma_f32_16x16x32_bf16 v[86:89], v[122:125], v[178:181], v[86:89]
	v_mfma_f32_16x16x32_bf16 v[22:25], v[130:133], v[178:181], v[22:25]
	v_mfma_f32_16x16x32_bf16 v[78:81], v[122:125], v[186:189], v[78:81]
	v_mfma_f32_16x16x32_bf16 v[10:13], v[130:133], v[186:189], v[10:13]
	v_mfma_f32_16x16x32_bf16 v[70:73], v[122:125], v[216:219], v[70:73]
	v_mfma_f32_16x16x32_bf16 v[2:5], v[130:133], v[216:219], v[2:5]
	s_barrier
	s_setprio 0
	s_add_i32 s54, s54, 2
	s_add_u32 s6, s6, 0x100
	s_addc_u32 s7, s7, 0
	s_add_u32 s52, s52, 0x100
	s_addc_u32 s53, s53, 0
	s_cmp_gt_u32 s54, 13
	s_cbranch_scc0 .LBB0_786
	v_readlane_b32 s6, v255, 19
	v_readlane_b32 s7, v255, 20
	s_mov_b64 s[46:47], s[82:83]
	s_and_b64 vcc, exec, s[6:7]
	s_cbranch_vccz .LBB0_789
	s_barrier

; #define PG8_STAGE(bufoff, gbase, voff) do { _Pragma("unroll") for (int _i = 0; _i < 2; ++_i) \
;         __builtin_amdgcn_global_load_lds((const unsigned*)((const char*)(gbase) + (voff)[_i]), (LAS unsigned*)(lds + (bufoff) + ldsw + _i * 8192), 16, 0, 0); } while (0)
; #define PG8_LDA(dst, b, h) do { _Pragma("unroll") for (int m = 0; m < 4; ++m) _Pragma("unroll") for (int k = 0; k < 2; ++k) dst[m][k] = *(const LAS bf16x8*)(lds + PG8_SA(b, h) + aoff + m * 2048 + k * 1024); } while (0)
; #define PG8_LDB(dst, b, h) do { _Pragma("unroll") for (int n = 0; n < 2; ++n) _Pragma("unroll") for (int k = 0; k < 2; ++k) dst[n][k] = *(const LAS bf16x8*)(lds + PG8_SB(b, h) + boff + n * 2048 + k * 1024); } while (0)
; #define PG8_WAIT_V(n) asm volatile("s_waitcnt vmcnt(" #n ")" ::: "memory")
; #define PG8_BAR __builtin_amdgcn_s_barrier()
; template <class Epi, bool SEG>
; __device__ __forceinline__ void gemm_phase(LAS unsigned char* lds, const Gemm g, const int G, const int cidx, const Epi& E) {
;     ...
;         for (int t = 0; t < nt; t += 2) {
;             const bool last = (t == nt - 2);
;             const char* a1 = cA + (size_t)(t + 1) * kstep;
;             const char* a2 = last ? nA : cA + (size_t)(t + 2) * kstep; const char* b2 = last ? nB : cB + (size_t)(t + 2) * kstep;
;             const char* a3 = a2 + kstep; const char* b3 = b2 + kstep;
;             PG8_LDB(B0, 0, 0); PG8_LDB(B1, 0, 1); PG8_SCHED; PG8_LDA(At, 0, 0); PG8_STAGE(PG8_SA(1, 1), a1 + hstepA, voffA);
;             PG8_WAIT_V(8); PG8_WAIT_L(0); PG8_BAR; PG8_MMA(0, 0, At, B0); PG8_MMA(0, 1, At, B1); PG8_BAR; PG8_SCHED;
;             PG8_LDA(At, 0, 1); PG8_STAGE(PG8_SB(0, 0), b2, voffB); PG8_STAGE(PG8_SB(0, 1), b2 + hstepB, voffB); PG8_STAGE(PG8_SA(0, 0), a2, voffA);
;             PG8_WAIT_V(8); PG8_WAIT_L(0); PG8_BAR; PG8_MMA(1, 0, At, B0); PG8_MMA(1, 1, At, B1); PG8_BAR; PG8_SCHED;
;             PG8_LDB(B0, 1, 0); PG8_LDB(B1, 1, 1); PG8_SCHED; PG8_LDA(At, 1, 0); PG8_STAGE(PG8_SA(0, 1), a2 + hstepA, voffA);
;             PG8_WAIT_V(8); PG8_WAIT_L(0); PG8_BAR; PG8_MMA(0, 0, At, B0); PG8_MMA(0, 1, At, B1); PG8_BAR; PG8_SCHED;
;             PG8_LDA(At, 1, 1); PG8_STAGE(PG8_SB(1, 0), b3, voffB); PG8_STAGE(PG8_SB(1, 1), b3 + hstepB, voffB); PG8_STAGE(PG8_SA(1, 0), a3, voffA);
;             PG8_WAIT_V(8); PG8_WAIT_L(0); PG8_BAR; PG8_MMA(1, 0, At, B0); PG8_MMA(1, 1, At, B1); PG8_BAR; PG8_SCHED;
.LBB0_958:
	s_add_u32 s20, s18, 0x100
	s_addc_u32 s21, s19, 0
	s_add_i32 s55, 0, 0x10000
	s_cmp_eq_u32 s54, 40
	s_cselect_b32 s47, s7, s21
	s_cselect_b32 s46, s6, s20
	s_cselect_b32 s23, s17, s53
	s_cselect_b32 s22, s16, s52
	s_add_i32 s56, 0, 0x14000
	v_add_u32_e32 v146, s55, v228
	v_add_u32_e32 v162, s56, v228
	ds_read_b128 v[130:133], v146
	ds_read_b128 v[138:141], v146 offset:1024
	ds_read_b128 v[142:145], v146 offset:2048
	ds_read_b128 v[146:149], v146 offset:3072
	ds_read_b128 v[150:153], v162
	ds_read_b128 v[154:157], v162 offset:1024
	ds_read_b128 v[158:161], v162 offset:2048
	ds_read_b128 v[162:165], v162 offset:3072
	v_lshl_add_u64 v[208:209], s[18:19], 0, v[198:199]
	s_add_i32 m0, s30, 0xc000
	ds_read_b128 v[166:169], v244
	ds_read_b128 v[170:173], v244 offset:1024
	ds_read_b128 v[174:177], v244 offset:2048
	ds_read_b128 v[178:181], v244 offset:3072
	ds_read_b128 v[182:185], v244 offset:4096
	ds_read_b128 v[186:189], v244 offset:5120
	ds_read_b128 v[190:193], v244 offset:6144
	ds_read_b128 v[212:215], v244 offset:7168
	global_load_lds_dwordx4 v[208:209], off
	v_lshl_add_u64 v[208:209], s[18:19], 0, v[200:201]
	s_add_i32 m0, s30, 0xe000
	s_nop 0
	global_load_lds_dwordx4 v[208:209], off
	s_waitcnt vmcnt(8)
	s_waitcnt lgkmcnt(0)
	s_setprio 1
	s_barrier
	v_mfma_f32_16x16x32_bf16 v[134:137], v[130:133], v[166:169], v[134:137]
	v_mfma_f32_16x16x32_bf16 v[126:129], v[142:145], v[166:169], v[126:129]
	v_mfma_f32_16x16x32_bf16 v[114:117], v[130:133], v[174:177], v[114:117]
	v_mfma_f32_16x16x32_bf16 v[110:113], v[142:145], v[174:177], v[110:113]
	v_mfma_f32_16x16x32_bf16 v[98:101], v[130:133], v[182:185], v[98:101]
	v_mfma_f32_16x16x32_bf16 v[94:97], v[142:145], v[182:185], v[94:97]
	v_mfma_f32_16x16x32_bf16 v[82:85], v[130:133], v[190:193], v[82:85]
	v_mfma_f32_16x16x32_bf16 v[78:81], v[142:145], v[190:193], v[78:81]
	v_mfma_f32_16x16x32_bf16 v[134:137], v[138:141], v[170:173], v[134:137]
	v_mfma_f32_16x16x32_bf16 v[126:129], v[146:149], v[170:173], v[126:129]
	v_mfma_f32_16x16x32_bf16 v[114:117], v[138:141], v[178:181], v[114:117]
	v_mfma_f32_16x16x32_bf16 v[110:113], v[146:149], v[178:181], v[110:113]
	v_mfma_f32_16x16x32_bf16 v[98:101], v[138:141], v[186:189], v[98:101]
	v_mfma_f32_16x16x32_bf16 v[94:97], v[146:149], v[186:189], v[94:97]
	v_mfma_f32_16x16x32_bf16 v[82:85], v[138:141], v[212:215], v[82:85]
	v_mfma_f32_16x16x32_bf16 v[78:81], v[146:149], v[212:215], v[78:81]
	s_setprio 0
	s_setprio 1
	v_mfma_f32_16x16x32_bf16 v[122:125], v[150:153], v[166:169], v[122:125]
	v_mfma_f32_16x16x32_bf16 v[118:121], v[158:161], v[166:169], v[118:121]
	v_mfma_f32_16x16x32_bf16 v[106:109], v[150:153], v[174:177], v[106:109]
	v_mfma_f32_16x16x32_bf16 v[102:105], v[158:161], v[174:177], v[102:105]
	v_mfma_f32_16x16x32_bf16 v[90:93], v[150:153], v[182:185], v[90:93]
	v_mfma_f32_16x16x32_bf16 v[86:89], v[158:161], v[182:185], v[86:89]
	v_mfma_f32_16x16x32_bf16 v[74:77], v[150:153], v[190:193], v[74:77]
	v_mfma_f32_16x16x32_bf16 v[70:73], v[158:161], v[190:193], v[70:73]
	v_mfma_f32_16x16x32_bf16 v[122:125], v[154:157], v[170:173], v[122:125]
	v_mfma_f32_16x16x32_bf16 v[118:121], v[162:165], v[170:173], v[118:121]
	v_mfma_f32_16x16x32_bf16 v[106:109], v[154:157], v[178:181], v[106:109]
	v_mfma_f32_16x16x32_bf16 v[102:105], v[162:165], v[178:181], v[102:105]
	v_mfma_f32_16x16x32_bf16 v[90:93], v[154:157], v[186:189], v[90:93]
	v_mfma_f32_16x16x32_bf16 v[86:89], v[162:165], v[186:189], v[86:89]
	v_mfma_f32_16x16x32_bf16 v[74:77], v[154:157], v[212:215], v[74:77]
	v_mfma_f32_16x16x32_bf16 v[70:73], v[162:165], v[212:215], v[70:73]
	s_barrier
	s_setprio 0
	s_add_i32 s18, s55, s9
	v_lshl_add_u64 v[208:209], s[22:23], 0, v[0:1]
	s_mov_b32 m0, s18
	ds_read_b128 v[166:169], v244 offset:16384
	ds_read_b128 v[170:173], v244 offset:17408
	ds_read_b128 v[174:177], v244 offset:18432
	ds_read_b128 v[178:181], v244 offset:19456
	ds_read_b128 v[182:185], v244 offset:20480
	ds_read_b128 v[186:189], v244 offset:21504
	ds_read_b128 v[190:193], v244 offset:22528
	ds_read_b128 v[212:215], v244 offset:23552
	global_load_lds_dwordx4 v[208:209], off
	s_add_i32 m0, s18, 0x2000
	s_add_u32 s18, s22, 0xb0000
	v_lshl_add_u64 v[216:217], s[22:23], 0, v[14:15]
	s_addc_u32 s19, s23, 0
	s_add_i32 s55, s56, s9
	global_load_lds_dwordx4 v[216:217], off
	v_lshl_add_u64 v[218:219], s[18:19], 0, v[0:1]
	s_mov_b32 m0, s55
	v_lshl_add_u64 v[220:221], s[46:47], 0, v[194:195]
	global_load_lds_dwordx4 v[218:219], off
	v_lshl_add_u64 v[218:219], s[18:19], 0, v[14:15]
	s_add_i32 m0, s55, 0x2000
	s_nop 0
	global_load_lds_dwordx4 v[218:219], off
	v_lshl_add_u64 v[218:219], s[46:47], 0, v[196:197]
	s_mov_b32 m0, s30
	s_nop 0
	global_load_lds_dwordx4 v[218:219], off
	s_mov_b32 m0, s31
	s_nop 0
	global_load_lds_dwordx4 v[220:221], off
	s_waitcnt vmcnt(8)
	s_waitcnt lgkmcnt(0)
	s_setprio 1
	s_barrier
; #define PG8_STAGE(bufoff, gbase, voff) do { _Pragma("unroll") for (int _i = 0; _i < 2; ++_i) \
;         __builtin_amdgcn_global_load_lds((const unsigned*)((const char*)(gbase) + (voff)[_i]), (LAS unsigned*)(lds + (bufoff) + ldsw + _i * 8192), 16, 0, 0); } while (0)
; #define PG8_LDA(dst, b, h) do { _Pragma("unroll") for (int m = 0; m < 4; ++m) _Pragma("unroll") for (int k = 0; k < 2; ++k) dst[m][k] = *(const LAS bf16x8*)(lds + PG8_SA(b, h) + aoff + m * 2048 + k * 1024); } while (0)
; #define PG8_LDB(dst, b, h) do { _Pragma("unroll") for (int n = 0; n < 2; ++n) _Pragma("unroll") for (int k = 0; k < 2; ++k) dst[n][k] = *(const LAS bf16x8*)(lds + PG8_SB(b, h) + boff + n * 2048 + k * 1024); } while (0)
; #define PG8_MMA(ai, bj, At, Bt) do { __builtin_amdgcn_s_setprio(1); _Pragma("unroll") for (int m = 0; m < 4; ++m) _Pragma("unroll") for (int n = 0; n < 2; ++n) _Pragma("unroll") for (int k = 0; k < 2; ++k) \
;         acc[ai][bj][m][n] = __builtin_amdgcn_mfma_f32_16x16x32_bf16(Bt[n][k], At[m][k], acc[ai][bj][m][n], 0, 0, 0); __builtin_amdgcn_s_setprio(0); } while (0)
; #define PG8_WAIT_V(n) asm volatile("s_waitcnt vmcnt(" #n ")" ::: "memory")
; #define PG8_WAIT_L(n) asm volatile("s_waitcnt lgkmcnt(" #n ")" ::: "memory")
; #define PG8_BAR __builtin_amdgcn_s_barrier()
; #define PG8_SCHED __builtin_amdgcn_sched_barrier(0)
; template <class Epi, bool SEG>
; __device__ __forceinline__ void gemm_phase(LAS unsigned char* lds, const Gemm g, const int G, const int cidx, const Epi& E) {
;     ...
;             PG8_LDA(At, 0, 1); PG8_STAGE(PG8_SB(0, 0), b2, voffB); PG8_STAGE(PG8_SB(0, 1), b2 + hstepB, voffB); PG8_STAGE(PG8_SA(0, 0), a2, voffA);
;             PG8_WAIT_V(8); PG8_WAIT_L(0); PG8_BAR; PG8_MMA(1, 0, At, B0); PG8_MMA(1, 1, At, B1); PG8_BAR; PG8_SCHED;
;             PG8_LDB(B0, 1, 0); PG8_LDB(B1, 1, 1); PG8_SCHED; PG8_LDA(At, 1, 0); PG8_STAGE(PG8_SA(0, 1), a2 + hstepA, voffA);
;             PG8_WAIT_V(8); PG8_WAIT_L(0); PG8_BAR; PG8_MMA(0, 0, At, B0); PG8_MMA(0, 1, At, B1); PG8_BAR; PG8_SCHED;
;             PG8_LDA(At, 1, 1); PG8_STAGE(PG8_SB(1, 0), b3, voffB); PG8_STAGE(PG8_SB(1, 1), b3 + hstepB, voffB); PG8_STAGE(PG8_SA(1, 0), a3, voffA);
;             PG8_WAIT_V(8); PG8_WAIT_L(0); PG8_BAR; PG8_MMA(1, 0, At, B0); PG8_MMA(1, 1, At, B1); PG8_BAR; PG8_SCHED;
	v_mfma_f32_16x16x32_bf16 v[66:69], v[130:133], v[166:169], v[66:69]
	v_mfma_f32_16x16x32_bf16 v[62:65], v[142:145], v[166:169], v[62:65]
	v_mfma_f32_16x16x32_bf16 v[50:53], v[130:133], v[174:177], v[50:53]
	v_mfma_f32_16x16x32_bf16 v[46:49], v[142:145], v[174:177], v[46:49]
	v_mfma_f32_16x16x32_bf16 v[34:37], v[130:133], v[182:185], v[34:37]
	v_mfma_f32_16x16x32_bf16 v[30:33], v[142:145], v[182:185], v[30:33]
	v_mfma_f32_16x16x32_bf16 v[18:21], v[130:133], v[190:193], v[18:21]
	v_mfma_f32_16x16x32_bf16 v[10:13], v[142:145], v[190:193], v[10:13]
	v_mfma_f32_16x16x32_bf16 v[66:69], v[138:141], v[170:173], v[66:69]
	v_mfma_f32_16x16x32_bf16 v[62:65], v[146:149], v[170:173], v[62:65]
	v_mfma_f32_16x16x32_bf16 v[50:53], v[138:141], v[178:181], v[50:53]
	v_mfma_f32_16x16x32_bf16 v[46:49], v[146:149], v[178:181], v[46:49]
	v_mfma_f32_16x16x32_bf16 v[34:37], v[138:141], v[186:189], v[34:37]
	v_mfma_f32_16x16x32_bf16 v[30:33], v[146:149], v[186:189], v[30:33]
	v_mfma_f32_16x16x32_bf16 v[18:21], v[138:141], v[212:215], v[18:21]
	v_mfma_f32_16x16x32_bf16 v[10:13], v[146:149], v[212:215], v[10:13]
	s_setprio 0
	s_setprio 1
	v_mfma_f32_16x16x32_bf16 v[58:61], v[150:153], v[166:169], v[58:61]
	v_mfma_f32_16x16x32_bf16 v[54:57], v[158:161], v[166:169], v[54:57]
	v_mfma_f32_16x16x32_bf16 v[42:45], v[150:153], v[174:177], v[42:45]
	v_mfma_f32_16x16x32_bf16 v[38:41], v[158:161], v[174:177], v[38:41]
	v_mfma_f32_16x16x32_bf16 v[26:29], v[150:153], v[182:185], v[26:29]
	v_mfma_f32_16x16x32_bf16 v[22:25], v[158:161], v[182:185], v[22:25]
	v_mfma_f32_16x16x32_bf16 v[6:9], v[150:153], v[190:193], v[6:9]
	v_mfma_f32_16x16x32_bf16 v[2:5], v[158:161], v[190:193], v[2:5]
	v_mfma_f32_16x16x32_bf16 v[58:61], v[154:157], v[170:173], v[58:61]
	v_mfma_f32_16x16x32_bf16 v[54:57], v[162:165], v[170:173], v[54:57]
	v_mfma_f32_16x16x32_bf16 v[42:45], v[154:157], v[178:181], v[42:45]
	v_mfma_f32_16x16x32_bf16 v[38:41], v[162:165], v[178:181], v[38:41]
	v_mfma_f32_16x16x32_bf16 v[26:29], v[154:157], v[186:189], v[26:29]
	v_mfma_f32_16x16x32_bf16 v[22:25], v[162:165], v[186:189], v[22:25]
	v_mfma_f32_16x16x32_bf16 v[6:9], v[154:157], v[212:215], v[6:9]
	v_mfma_f32_16x16x32_bf16 v[2:5], v[162:165], v[212:215], v[2:5]
	s_barrier
	s_setprio 0
	s_add_i32 s55, 0, 0x18000
	s_add_i32 s56, 0, 0x1c000
	v_add_u32_e32 v146, s55, v228
	v_add_u32_e32 v162, s56, v228
	ds_read_b128 v[130:133], v146
	ds_read_b128 v[138:141], v146 offset:1024
	ds_read_b128 v[142:145], v146 offset:2048
	ds_read_b128 v[146:149], v146 offset:3072
	ds_read_b128 v[150:153], v162
	ds_read_b128 v[154:157], v162 offset:1024
	ds_read_b128 v[158:161], v162 offset:2048
	ds_read_b128 v[162:165], v162 offset:3072
	s_add_u32 s18, s46, 0xb0000
	s_addc_u32 s19, s47, 0
	s_mov_b32 m0, s36
	v_lshl_add_u64 v[222:223], s[18:19], 0, v[196:197]
	ds_read_b128 v[166:169], v244 offset:32768
	ds_read_b128 v[170:173], v244 offset:33792
	ds_read_b128 v[174:177], v244 offset:34816
	ds_read_b128 v[178:181], v244 offset:35840
	ds_read_b128 v[182:185], v244 offset:36864
	ds_read_b128 v[186:189], v244 offset:37888
	ds_read_b128 v[190:193], v244 offset:38912
	ds_read_b128 v[212:215], v244 offset:39936
	global_load_lds_dwordx4 v[222:223], off
	v_lshl_add_u64 v[222:223], s[18:19], 0, v[194:195]
	s_mov_b32 m0, s38
	s_nop 0
	global_load_lds_dwordx4 v[222:223], off
	s_waitcnt vmcnt(8)
	s_waitcnt lgkmcnt(0)
	s_setprio 1
	s_barrier
	v_mfma_f32_16x16x32_bf16 v[134:137], v[130:133], v[166:169], v[134:137]
	v_mfma_f32_16x16x32_bf16 v[126:129], v[142:145], v[166:169], v[126:129]
	v_mfma_f32_16x16x32_bf16 v[114:117], v[130:133], v[174:177], v[114:117]
	v_mfma_f32_16x16x32_bf16 v[110:113], v[142:145], v[174:177], v[110:113]
	v_mfma_f32_16x16x32_bf16 v[98:101], v[130:133], v[182:185], v[98:101]
	v_mfma_f32_16x16x32_bf16 v[94:97], v[142:145], v[182:185], v[94:97]
	v_mfma_f32_16x16x32_bf16 v[82:85], v[130:133], v[190:193], v[82:85]
	v_mfma_f32_16x16x32_bf16 v[78:81], v[142:145], v[190:193], v[78:81]
	v_mfma_f32_16x16x32_bf16 v[134:137], v[138:141], v[170:173], v[134:137]
	v_mfma_f32_16x16x32_bf16 v[126:129], v[146:149], v[170:173], v[126:129]
	v_mfma_f32_16x16x32_bf16 v[114:117], v[138:141], v[178:181], v[114:117]
	v_mfma_f32_16x16x32_bf16 v[110:113], v[146:149], v[178:181], v[110:113]
	v_mfma_f32_16x16x32_bf16 v[98:101], v[138:141], v[186:189], v[98:101]
	v_mfma_f32_16x16x32_bf16 v[94:97], v[146:149], v[186:189], v[94:97]
	v_mfma_f32_16x16x32_bf16 v[82:85], v[138:141], v[212:215], v[82:85]
	v_mfma_f32_16x16x32_bf16 v[78:81], v[146:149], v[212:215], v[78:81]
	s_setprio 0
	s_setprio 1
	v_mfma_f32_16x16x32_bf16 v[122:125], v[150:153], v[166:169], v[122:125]
	v_mfma_f32_16x16x32_bf16 v[118:121], v[158:161], v[166:169], v[118:121]
	v_mfma_f32_16x16x32_bf16 v[106:109], v[150:153], v[174:177], v[106:109]
	v_mfma_f32_16x16x32_bf16 v[102:105], v[158:161], v[174:177], v[102:105]
	v_mfma_f32_16x16x32_bf16 v[90:93], v[150:153], v[182:185], v[90:93]
	v_mfma_f32_16x16x32_bf16 v[86:89], v[158:161], v[182:185], v[86:89]
	v_mfma_f32_16x16x32_bf16 v[74:77], v[150:153], v[190:193], v[74:77]
	v_mfma_f32_16x16x32_bf16 v[70:73], v[158:161], v[190:193], v[70:73]
	v_mfma_f32_16x16x32_bf16 v[122:125], v[154:157], v[170:173], v[122:125]
	v_mfma_f32_16x16x32_bf16 v[118:121], v[162:165], v[170:173], v[118:121]
	v_mfma_f32_16x16x32_bf16 v[106:109], v[154:157], v[178:181], v[106:109]
	v_mfma_f32_16x16x32_bf16 v[102:105], v[162:165], v[178:181], v[102:105]
	v_mfma_f32_16x16x32_bf16 v[90:93], v[154:157], v[186:189], v[90:93]
	v_mfma_f32_16x16x32_bf16 v[86:89], v[162:165], v[186:189], v[86:89]
	v_mfma_f32_16x16x32_bf16 v[74:77], v[154:157], v[212:215], v[74:77]
	v_mfma_f32_16x16x32_bf16 v[70:73], v[162:165], v[212:215], v[70:73]
	s_barrier
; #define PG8_STAGE(bufoff, gbase, voff) do { _Pragma("unroll") for (int _i = 0; _i < 2; ++_i) \
;         __builtin_amdgcn_global_load_lds((const unsigned*)((const char*)(gbase) + (voff)[_i]), (LAS unsigned*)(lds + (bufoff) + ldsw + _i * 8192), 16, 0, 0); } while (0)
; #define PG8_LDA(dst, b, h) do { _Pragma("unroll") for (int m = 0; m < 4; ++m) _Pragma("unroll") for (int k = 0; k < 2; ++k) dst[m][k] = *(const LAS bf16x8*)(lds + PG8_SA(b, h) + aoff + m * 2048 + k * 1024); } while (0)
; #define PG8_LDB(dst, b, h) do { _Pragma("unroll") for (int n = 0; n < 2; ++n) _Pragma("unroll") for (int k = 0; k < 2; ++k) dst[n][k] = *(const LAS bf16x8*)(lds + PG8_SB(b, h) + boff + n * 2048 + k * 1024); } while (0)
; #define PG8_MMA(ai, bj, At, Bt) do { __builtin_amdgcn_s_setprio(1); _Pragma("unroll") for (int m = 0; m < 4; ++m) _Pragma("unroll") for (int n = 0; n < 2; ++n) _Pragma("unroll") for (int k = 0; k < 2; ++k) \
;         acc[ai][bj][m][n] = __builtin_amdgcn_mfma_f32_16x16x32_bf16(Bt[n][k], At[m][k], acc[ai][bj][m][n], 0, 0, 0); __builtin_amdgcn_s_setprio(0); } while (0)
; #define PG8_WAIT_V(n) asm volatile("s_waitcnt vmcnt(" #n ")" ::: "memory")
; #define PG8_WAIT_L(n) asm volatile("s_waitcnt lgkmcnt(" #n ")" ::: "memory")
; #define PG8_BAR __builtin_amdgcn_s_barrier()
; #define PG8_SCHED __builtin_amdgcn_sched_barrier(0)
; template <class Epi, bool SEG>
; __device__ __forceinline__ void gemm_phase(LAS unsigned char* lds, const Gemm g, const int G, const int cidx, const Epi& E) {
;     ...
;             PG8_LDB(B0, 1, 0); PG8_LDB(B1, 1, 1); PG8_SCHED; PG8_LDA(At, 1, 0); PG8_STAGE(PG8_SA(0, 1), a2 + hstepA, voffA);
;             PG8_WAIT_V(8); PG8_WAIT_L(0); PG8_BAR; PG8_MMA(0, 0, At, B0); PG8_MMA(0, 1, At, B1); PG8_BAR; PG8_SCHED;
;             PG8_LDA(At, 1, 1); PG8_STAGE(PG8_SB(1, 0), b3, voffB); PG8_STAGE(PG8_SB(1, 1), b3 + hstepB, voffB); PG8_STAGE(PG8_SA(1, 0), a3, voffA);
;             PG8_WAIT_V(8); PG8_WAIT_L(0); PG8_BAR; PG8_MMA(1, 0, At, B0); PG8_MMA(1, 1, At, B1); PG8_BAR; PG8_SCHED;
;         }
;         if (wr == 0) PG8_BAR;
	s_setprio 0
	s_add_i32 s18, s55, s9
	v_lshl_add_u64 v[208:209], v[208:209], 0, s[28:29]
	s_mov_b32 m0, s18
	ds_read_b128 v[166:169], v244 offset:49152
	ds_read_b128 v[170:173], v244 offset:50176
	ds_read_b128 v[174:177], v244 offset:51200
	ds_read_b128 v[178:181], v244 offset:52224
	ds_read_b128 v[182:185], v244 offset:53248
	ds_read_b128 v[186:189], v244 offset:54272
	ds_read_b128 v[190:193], v244 offset:55296
	ds_read_b128 v[212:215], v244 offset:56320
	global_load_lds_dwordx4 v[208:209], off
	s_add_i32 m0, s18, 0x2000
	s_add_u32 s18, s22, 0xb0080
	v_lshl_add_u64 v[208:209], v[216:217], 0, s[28:29]
	s_addc_u32 s19, s23, 0
	s_add_i32 s22, s56, s9
	global_load_lds_dwordx4 v[208:209], off
	v_lshl_add_u64 v[208:209], s[18:19], 0, v[0:1]
	s_mov_b32 m0, s22
	s_nop 0
	global_load_lds_dwordx4 v[208:209], off
	v_lshl_add_u64 v[208:209], s[18:19], 0, v[14:15]
	s_add_i32 m0, s22, 0x2000
	s_nop 0
	global_load_lds_dwordx4 v[208:209], off
	v_lshl_add_u64 v[208:209], v[218:219], 0, s[28:29]
	s_mov_b32 m0, s39
	s_nop 0
	global_load_lds_dwordx4 v[208:209], off
	v_lshl_add_u64 v[208:209], v[220:221], 0, s[28:29]
	s_mov_b32 m0, s48
	s_nop 0
	global_load_lds_dwordx4 v[208:209], off
	s_waitcnt vmcnt(8)
	s_waitcnt lgkmcnt(0)
	s_setprio 1
	s_barrier
	v_mfma_f32_16x16x32_bf16 v[66:69], v[130:133], v[166:169], v[66:69]
	v_mfma_f32_16x16x32_bf16 v[62:65], v[142:145], v[166:169], v[62:65]
	v_mfma_f32_16x16x32_bf16 v[50:53], v[130:133], v[174:177], v[50:53]
	v_mfma_f32_16x16x32_bf16 v[46:49], v[142:145], v[174:177], v[46:49]
	v_mfma_f32_16x16x32_bf16 v[34:37], v[130:133], v[182:185], v[34:37]
	v_mfma_f32_16x16x32_bf16 v[30:33], v[142:145], v[182:185], v[30:33]
	v_mfma_f32_16x16x32_bf16 v[18:21], v[130:133], v[190:193], v[18:21]
	v_mfma_f32_16x16x32_bf16 v[10:13], v[142:145], v[190:193], v[10:13]
	v_mfma_f32_16x16x32_bf16 v[66:69], v[138:141], v[170:173], v[66:69]
	v_mfma_f32_16x16x32_bf16 v[62:65], v[146:149], v[170:173], v[62:65]
	v_mfma_f32_16x16x32_bf16 v[50:53], v[138:141], v[178:181], v[50:53]
	v_mfma_f32_16x16x32_bf16 v[46:49], v[146:149], v[178:181], v[46:49]
	v_mfma_f32_16x16x32_bf16 v[34:37], v[138:141], v[186:189], v[34:37]
	v_mfma_f32_16x16x32_bf16 v[30:33], v[146:149], v[186:189], v[30:33]
	v_mfma_f32_16x16x32_bf16 v[18:21], v[138:141], v[212:215], v[18:21]
	v_mfma_f32_16x16x32_bf16 v[10:13], v[146:149], v[212:215], v[10:13]
	s_setprio 0
	s_setprio 1
	v_mfma_f32_16x16x32_bf16 v[58:61], v[150:153], v[166:169], v[58:61]
	v_mfma_f32_16x16x32_bf16 v[54:57], v[158:161], v[166:169], v[54:57]
	v_mfma_f32_16x16x32_bf16 v[42:45], v[150:153], v[174:177], v[42:45]
	v_mfma_f32_16x16x32_bf16 v[38:41], v[158:161], v[174:177], v[38:41]
	v_mfma_f32_16x16x32_bf16 v[26:29], v[150:153], v[182:185], v[26:29]
	v_mfma_f32_16x16x32_bf16 v[22:25], v[158:161], v[182:185], v[22:25]
	v_mfma_f32_16x16x32_bf16 v[6:9], v[150:153], v[190:193], v[6:9]
	v_mfma_f32_16x16x32_bf16 v[2:5], v[158:161], v[190:193], v[2:5]
	v_mfma_f32_16x16x32_bf16 v[58:61], v[154:157], v[170:173], v[58:61]
	v_mfma_f32_16x16x32_bf16 v[54:57], v[162:165], v[170:173], v[54:57]
	v_mfma_f32_16x16x32_bf16 v[42:45], v[154:157], v[178:181], v[42:45]
	v_mfma_f32_16x16x32_bf16 v[38:41], v[162:165], v[178:181], v[38:41]
	v_mfma_f32_16x16x32_bf16 v[26:29], v[154:157], v[186:189], v[26:29]
	v_mfma_f32_16x16x32_bf16 v[22:25], v[162:165], v[186:189], v[22:25]
	v_mfma_f32_16x16x32_bf16 v[6:9], v[154:157], v[212:215], v[6:9]
	v_mfma_f32_16x16x32_bf16 v[2:5], v[162:165], v[212:215], v[2:5]
	s_barrier
	s_setprio 0
	s_add_i32 s54, s54, 2
	s_add_u32 s52, s52, 0x100
	s_addc_u32 s53, s53, 0
	s_cmp_gt_u32 s54, 41
	s_mov_b64 s[18:19], s[20:21]
	s_cbranch_scc0 .LBB0_958
	s_and_b64 vcc, exec, s[12:13]
	s_cbranch_vccz .LBB0_961
	s_barrier

; #define PG8_STAGE(bufoff, gbase, voff) do { _Pragma("unroll") for (int _i = 0; _i < 2; ++_i) \
;         __builtin_amdgcn_global_load_lds((const unsigned*)((const char*)(gbase) + (voff)[_i]), (LAS unsigned*)(lds + (bufoff) + ldsw + _i * 8192), 16, 0, 0); } while (0)
; #define PG8_LDA(dst, b, h) do { _Pragma("unroll") for (int m = 0; m < 4; ++m) _Pragma("unroll") for (int k = 0; k < 2; ++k) dst[m][k] = *(const LAS bf16x8*)(lds + PG8_SA(b, h) + aoff + m * 2048 + k * 1024); } while (0)
; #define PG8_LDB(dst, b, h) do { _Pragma("unroll") for (int n = 0; n < 2; ++n) _Pragma("unroll") for (int k = 0; k < 2; ++k) dst[n][k] = *(const LAS bf16x8*)(lds + PG8_SB(b, h) + boff + n * 2048 + k * 1024); } while (0)
; #define PG8_WAIT_V(n) asm volatile("s_waitcnt vmcnt(" #n ")" ::: "memory")
; #define PG8_BAR __builtin_amdgcn_s_barrier()
; template <class Epi, bool SEG>
; __device__ __forceinline__ void gemm_phase(LAS unsigned char* lds, const Gemm g, const int G, const int cidx, const Epi& E) {
;     ...
;         for (int t = 0; t < nt; t += 2) {
;             const bool last = (t == nt - 2);
;             const char* a1 = cA + (size_t)(t + 1) * kstep;
;             const char* a2 = last ? nA : cA + (size_t)(t + 2) * kstep; const char* b2 = last ? nB : cB + (size_t)(t + 2) * kstep;
;             const char* a3 = a2 + kstep; const char* b3 = b2 + kstep;
;             PG8_LDB(B0, 0, 0); PG8_LDB(B1, 0, 1); PG8_SCHED; PG8_LDA(At, 0, 0); PG8_STAGE(PG8_SA(1, 1), a1 + hstepA, voffA);
;             PG8_WAIT_V(8); PG8_WAIT_L(0); PG8_BAR; PG8_MMA(0, 0, At, B0); PG8_MMA(0, 1, At, B1); PG8_BAR; PG8_SCHED;
;             PG8_LDA(At, 0, 1); PG8_STAGE(PG8_SB(0, 0), b2, voffB); PG8_STAGE(PG8_SB(0, 1), b2 + hstepB, voffB); PG8_STAGE(PG8_SA(0, 0), a2, voffA);
;             PG8_WAIT_V(8); PG8_WAIT_L(0); PG8_BAR; PG8_MMA(1, 0, At, B0); PG8_MMA(1, 1, At, B1); PG8_BAR; PG8_SCHED;
;             PG8_LDB(B0, 1, 0); PG8_LDB(B1, 1, 1); PG8_SCHED; PG8_LDA(At, 1, 0); PG8_STAGE(PG8_SA(0, 1), a2 + hstepA, voffA);
;             PG8_WAIT_V(8); PG8_WAIT_L(0); PG8_BAR; PG8_MMA(0, 0, At, B0); PG8_MMA(0, 1, At, B1); PG8_BAR; PG8_SCHED;
;             PG8_LDA(At, 1, 1); PG8_STAGE(PG8_SB(1, 0), b3, voffB); PG8_STAGE(PG8_SB(1, 1), b3 + hstepB, voffB); PG8_STAGE(PG8_SA(1, 0), a3, voffA);
;             PG8_WAIT_V(8); PG8_WAIT_L(0); PG8_BAR; PG8_MMA(1, 0, At, B0); PG8_MMA(1, 1, At, B1); PG8_BAR; PG8_SCHED;
.LBB0_1060:
	s_add_i32 s63, s42, 2
	s_add_u32 s40, s22, 0x100
	s_addc_u32 s41, s23, 0
	s_add_i32 s66, 0, 0x10000
	s_cmp_eq_u32 s57, s42
	s_cselect_b32 s43, s19, s41
	s_cselect_b32 s42, s18, s40
	v_add_u32_e32 v145, s66, v142
	s_cselect_b32 s65, s21, s62
	s_cselect_b32 s64, s20, s61
	s_add_i32 s67, 0, 0x14000
	ds_read_b128 v[146:149], v145
	ds_read_b128 v[150:153], v145 offset:1024
	ds_read_b128 v[154:157], v145 offset:2048
	ds_read_b128 v[158:161], v145 offset:3072
	v_add_u32_e32 v145, s67, v142
	ds_read_b128 v[162:165], v145
	ds_read_b128 v[166:169], v145 offset:1024
	ds_read_b128 v[170:173], v145 offset:2048
	ds_read_b128 v[174:177], v145 offset:3072
	v_lshl_add_u64 v[220:221], s[22:23], 0, v[138:139]
	s_add_i32 m0, s47, 0xc000
	ds_read_b128 v[178:181], v144
	ds_read_b128 v[182:185], v144 offset:1024
	ds_read_b128 v[186:189], v144 offset:2048
	ds_read_b128 v[190:193], v144 offset:3072
	ds_read_b128 v[194:197], v144 offset:4096
	ds_read_b128 v[198:201], v144 offset:5120
	ds_read_b128 v[212:215], v144 offset:6144
	ds_read_b128 v[216:219], v144 offset:7168
	global_load_lds_dwordx4 v[220:221], off
	v_lshl_add_u64 v[220:221], s[22:23], 0, v[140:141]
	s_add_i32 m0, s47, 0xe000
	s_nop 0
	global_load_lds_dwordx4 v[220:221], off
	s_waitcnt vmcnt(8)
	s_waitcnt lgkmcnt(0)
	s_setprio 1
	s_barrier
	v_mfma_f32_16x16x32_bf16 v[130:133], v[146:149], v[178:181], v[130:133]
	v_mfma_f32_16x16x32_bf16 v[126:129], v[154:157], v[178:181], v[126:129]
	v_mfma_f32_16x16x32_bf16 v[122:125], v[146:149], v[186:189], v[122:125]
	v_mfma_f32_16x16x32_bf16 v[118:121], v[154:157], v[186:189], v[118:121]
	v_mfma_f32_16x16x32_bf16 v[106:109], v[146:149], v[194:197], v[106:109]
	v_mfma_f32_16x16x32_bf16 v[102:105], v[154:157], v[194:197], v[102:105]
	v_mfma_f32_16x16x32_bf16 v[90:93], v[146:149], v[212:215], v[90:93]
	v_mfma_f32_16x16x32_bf16 v[86:89], v[154:157], v[212:215], v[86:89]
	v_mfma_f32_16x16x32_bf16 v[130:133], v[150:153], v[182:185], v[130:133]
	v_mfma_f32_16x16x32_bf16 v[126:129], v[158:161], v[182:185], v[126:129]
	v_mfma_f32_16x16x32_bf16 v[122:125], v[150:153], v[190:193], v[122:125]
	v_mfma_f32_16x16x32_bf16 v[118:121], v[158:161], v[190:193], v[118:121]
	v_mfma_f32_16x16x32_bf16 v[106:109], v[150:153], v[198:201], v[106:109]
	v_mfma_f32_16x16x32_bf16 v[102:105], v[158:161], v[198:201], v[102:105]
	v_mfma_f32_16x16x32_bf16 v[90:93], v[150:153], v[216:219], v[90:93]
	v_mfma_f32_16x16x32_bf16 v[86:89], v[158:161], v[216:219], v[86:89]
	s_setprio 0
	s_setprio 1
	v_mfma_f32_16x16x32_bf16 v[114:117], v[162:165], v[178:181], v[114:117]
	v_mfma_f32_16x16x32_bf16 v[110:113], v[170:173], v[178:181], v[110:113]
	v_mfma_f32_16x16x32_bf16 v[98:101], v[162:165], v[186:189], v[98:101]
	v_mfma_f32_16x16x32_bf16 v[94:97], v[170:173], v[186:189], v[94:97]
	v_mfma_f32_16x16x32_bf16 v[82:85], v[162:165], v[194:197], v[82:85]
	v_mfma_f32_16x16x32_bf16 v[78:81], v[170:173], v[194:197], v[78:81]
	v_mfma_f32_16x16x32_bf16 v[74:77], v[162:165], v[212:215], v[74:77]
	v_mfma_f32_16x16x32_bf16 v[70:73], v[170:173], v[212:215], v[70:73]
	v_mfma_f32_16x16x32_bf16 v[114:117], v[166:169], v[182:185], v[114:117]
	v_mfma_f32_16x16x32_bf16 v[110:113], v[174:177], v[182:185], v[110:113]
	v_mfma_f32_16x16x32_bf16 v[98:101], v[166:169], v[190:193], v[98:101]
	v_mfma_f32_16x16x32_bf16 v[94:97], v[174:177], v[190:193], v[94:97]
	v_mfma_f32_16x16x32_bf16 v[82:85], v[166:169], v[198:201], v[82:85]
	v_mfma_f32_16x16x32_bf16 v[78:81], v[174:177], v[198:201], v[78:81]
	v_mfma_f32_16x16x32_bf16 v[74:77], v[166:169], v[216:219], v[74:77]
	v_mfma_f32_16x16x32_bf16 v[70:73], v[174:177], v[216:219], v[70:73]
	s_barrier
	s_setprio 0
	s_add_i32 s22, s66, s39
	v_lshl_add_u64 v[220:221], s[64:65], 0, v[0:1]
	s_mov_b32 m0, s22
	ds_read_b128 v[178:181], v144 offset:16384
	ds_read_b128 v[182:185], v144 offset:17408
	ds_read_b128 v[186:189], v144 offset:18432
	ds_read_b128 v[190:193], v144 offset:19456
	ds_read_b128 v[194:197], v144 offset:20480
	ds_read_b128 v[198:201], v144 offset:21504
	ds_read_b128 v[212:215], v144 offset:22528
	ds_read_b128 v[216:219], v144 offset:23552
	global_load_lds_dwordx4 v[220:221], off
	s_add_i32 m0, s22, 0x2000
	s_add_u32 s22, s64, s31
	v_lshl_add_u64 v[222:223], s[64:65], 0, v[14:15]
	s_addc_u32 s23, s65, 0
	s_add_i32 s64, s67, s39
	global_load_lds_dwordx4 v[222:223], off
	v_lshl_add_u64 v[224:225], s[22:23], 0, v[0:1]
	s_mov_b32 m0, s64
	v_lshl_add_u64 v[226:227], s[22:23], 0, v[14:15]
	global_load_lds_dwordx4 v[224:225], off
	s_add_i32 m0, s64, 0x2000
	v_lshl_add_u64 v[228:229], s[42:43], 0, v[136:137]
	global_load_lds_dwordx4 v[226:227], off
	s_mov_b32 m0, s47
	v_lshl_add_u64 v[244:245], s[42:43], 0, v[134:135]
	global_load_lds_dwordx4 v[228:229], off
	s_mov_b32 m0, s48
	s_nop 0
	global_load_lds_dwordx4 v[244:245], off
	s_waitcnt vmcnt(8)
	s_waitcnt lgkmcnt(0)
	s_setprio 1
	s_barrier
; #define PG8_STAGE(bufoff, gbase, voff) do { _Pragma("unroll") for (int _i = 0; _i < 2; ++_i) \
;         __builtin_amdgcn_global_load_lds((const unsigned*)((const char*)(gbase) + (voff)[_i]), (LAS unsigned*)(lds + (bufoff) + ldsw + _i * 8192), 16, 0, 0); } while (0)
; #define PG8_LDA(dst, b, h) do { _Pragma("unroll") for (int m = 0; m < 4; ++m) _Pragma("unroll") for (int k = 0; k < 2; ++k) dst[m][k] = *(const LAS bf16x8*)(lds + PG8_SA(b, h) + aoff + m * 2048 + k * 1024); } while (0)
; #define PG8_LDB(dst, b, h) do { _Pragma("unroll") for (int n = 0; n < 2; ++n) _Pragma("unroll") for (int k = 0; k < 2; ++k) dst[n][k] = *(const LAS bf16x8*)(lds + PG8_SB(b, h) + boff + n * 2048 + k * 1024); } while (0)
; #define PG8_MMA(ai, bj, At, Bt) do { __builtin_amdgcn_s_setprio(1); _Pragma("unroll") for (int m = 0; m < 4; ++m) _Pragma("unroll") for (int n = 0; n < 2; ++n) _Pragma("unroll") for (int k = 0; k < 2; ++k) \
;         acc[ai][bj][m][n] = __builtin_amdgcn_mfma_f32_16x16x32_bf16(Bt[n][k], At[m][k], acc[ai][bj][m][n], 0, 0, 0); __builtin_amdgcn_s_setprio(0); } while (0)
; #define PG8_WAIT_V(n) asm volatile("s_waitcnt vmcnt(" #n ")" ::: "memory")
; #define PG8_WAIT_L(n) asm volatile("s_waitcnt lgkmcnt(" #n ")" ::: "memory")
; #define PG8_BAR __builtin_amdgcn_s_barrier()
; #define PG8_SCHED __builtin_amdgcn_sched_barrier(0)
; template <class Epi, bool SEG>
; __device__ __forceinline__ void gemm_phase(LAS unsigned char* lds, const Gemm g, const int G, const int cidx, const Epi& E) {
;     ...
;             PG8_LDA(At, 0, 1); PG8_STAGE(PG8_SB(0, 0), b2, voffB); PG8_STAGE(PG8_SB(0, 1), b2 + hstepB, voffB); PG8_STAGE(PG8_SA(0, 0), a2, voffA);
;             PG8_WAIT_V(8); PG8_WAIT_L(0); PG8_BAR; PG8_MMA(1, 0, At, B0); PG8_MMA(1, 1, At, B1); PG8_BAR; PG8_SCHED;
;             PG8_LDB(B0, 1, 0); PG8_LDB(B1, 1, 1); PG8_SCHED; PG8_LDA(At, 1, 0); PG8_STAGE(PG8_SA(0, 1), a2 + hstepA, voffA);
;             PG8_WAIT_V(8); PG8_WAIT_L(0); PG8_BAR; PG8_MMA(0, 0, At, B0); PG8_MMA(0, 1, At, B1); PG8_BAR; PG8_SCHED;
;             PG8_LDA(At, 1, 1); PG8_STAGE(PG8_SB(1, 0), b3, voffB); PG8_STAGE(PG8_SB(1, 1), b3 + hstepB, voffB); PG8_STAGE(PG8_SA(1, 0), a3, voffA);
;             PG8_WAIT_V(8); PG8_WAIT_L(0); PG8_BAR; PG8_MMA(1, 0, At, B0); PG8_MMA(1, 1, At, B1); PG8_BAR; PG8_SCHED;
	v_mfma_f32_16x16x32_bf16 v[66:69], v[146:149], v[178:181], v[66:69]
	v_mfma_f32_16x16x32_bf16 v[62:65], v[154:157], v[178:181], v[62:65]
	v_mfma_f32_16x16x32_bf16 v[58:61], v[146:149], v[186:189], v[58:61]
	v_mfma_f32_16x16x32_bf16 v[54:57], v[154:157], v[186:189], v[54:57]
	v_mfma_f32_16x16x32_bf16 v[42:45], v[146:149], v[194:197], v[42:45]
	v_mfma_f32_16x16x32_bf16 v[38:41], v[154:157], v[194:197], v[38:41]
	v_mfma_f32_16x16x32_bf16 v[26:29], v[146:149], v[212:215], v[26:29]
	v_mfma_f32_16x16x32_bf16 v[22:25], v[154:157], v[212:215], v[22:25]
	v_mfma_f32_16x16x32_bf16 v[66:69], v[150:153], v[182:185], v[66:69]
	v_mfma_f32_16x16x32_bf16 v[62:65], v[158:161], v[182:185], v[62:65]
	v_mfma_f32_16x16x32_bf16 v[58:61], v[150:153], v[190:193], v[58:61]
	v_mfma_f32_16x16x32_bf16 v[54:57], v[158:161], v[190:193], v[54:57]
	v_mfma_f32_16x16x32_bf16 v[42:45], v[150:153], v[198:201], v[42:45]
	v_mfma_f32_16x16x32_bf16 v[38:41], v[158:161], v[198:201], v[38:41]
	v_mfma_f32_16x16x32_bf16 v[26:29], v[150:153], v[216:219], v[26:29]
	v_mfma_f32_16x16x32_bf16 v[22:25], v[158:161], v[216:219], v[22:25]
	s_setprio 0
	s_setprio 1
	v_mfma_f32_16x16x32_bf16 v[50:53], v[162:165], v[178:181], v[50:53]
	v_mfma_f32_16x16x32_bf16 v[46:49], v[170:173], v[178:181], v[46:49]
	v_mfma_f32_16x16x32_bf16 v[34:37], v[162:165], v[186:189], v[34:37]
	v_mfma_f32_16x16x32_bf16 v[30:33], v[170:173], v[186:189], v[30:33]
	v_mfma_f32_16x16x32_bf16 v[18:21], v[162:165], v[194:197], v[18:21]
	v_mfma_f32_16x16x32_bf16 v[10:13], v[170:173], v[194:197], v[10:13]
	v_mfma_f32_16x16x32_bf16 v[6:9], v[162:165], v[212:215], v[6:9]
	v_mfma_f32_16x16x32_bf16 v[2:5], v[170:173], v[212:215], v[2:5]
	v_mfma_f32_16x16x32_bf16 v[50:53], v[166:169], v[182:185], v[50:53]
	v_mfma_f32_16x16x32_bf16 v[46:49], v[174:177], v[182:185], v[46:49]
	v_mfma_f32_16x16x32_bf16 v[34:37], v[166:169], v[190:193], v[34:37]
	v_mfma_f32_16x16x32_bf16 v[30:33], v[174:177], v[190:193], v[30:33]
	v_mfma_f32_16x16x32_bf16 v[18:21], v[166:169], v[198:201], v[18:21]
	v_mfma_f32_16x16x32_bf16 v[10:13], v[174:177], v[198:201], v[10:13]
	v_mfma_f32_16x16x32_bf16 v[6:9], v[166:169], v[216:219], v[6:9]
	v_mfma_f32_16x16x32_bf16 v[2:5], v[174:177], v[216:219], v[2:5]
	s_barrier
	s_setprio 0
	s_add_i32 s64, 0, 0x18000
	v_add_u32_e32 v145, s64, v142
	s_add_i32 s65, 0, 0x1c000
	ds_read_b128 v[146:149], v145
	ds_read_b128 v[150:153], v145 offset:1024
	ds_read_b128 v[154:157], v145 offset:2048
	ds_read_b128 v[158:161], v145 offset:3072
	v_add_u32_e32 v145, s65, v142
	ds_read_b128 v[162:165], v145
	ds_read_b128 v[166:169], v145 offset:1024
	ds_read_b128 v[170:173], v145 offset:2048
	ds_read_b128 v[174:177], v145 offset:3072
	s_add_u32 s22, s42, 0x30000
	s_addc_u32 s23, s43, 0
	s_mov_b32 m0, s49
	v_lshl_add_u64 v[246:247], s[22:23], 0, v[136:137]
	ds_read_b128 v[178:181], v144 offset:32768
	ds_read_b128 v[182:185], v144 offset:33792
	ds_read_b128 v[186:189], v144 offset:34816
	ds_read_b128 v[190:193], v144 offset:35840
	ds_read_b128 v[194:197], v144 offset:36864
	ds_read_b128 v[198:201], v144 offset:37888
	ds_read_b128 v[212:215], v144 offset:38912
	ds_read_b128 v[216:219], v144 offset:39936
	global_load_lds_dwordx4 v[246:247], off
	v_lshl_add_u64 v[246:247], s[22:23], 0, v[134:135]
	s_mov_b32 m0, s50
	s_nop 0
	global_load_lds_dwordx4 v[246:247], off
	s_waitcnt vmcnt(8)
	s_waitcnt lgkmcnt(0)
	s_setprio 1
	s_barrier
	v_mfma_f32_16x16x32_bf16 v[130:133], v[146:149], v[178:181], v[130:133]
	v_mfma_f32_16x16x32_bf16 v[126:129], v[154:157], v[178:181], v[126:129]
	v_mfma_f32_16x16x32_bf16 v[122:125], v[146:149], v[186:189], v[122:125]
	v_mfma_f32_16x16x32_bf16 v[118:121], v[154:157], v[186:189], v[118:121]
	v_mfma_f32_16x16x32_bf16 v[106:109], v[146:149], v[194:197], v[106:109]
	v_mfma_f32_16x16x32_bf16 v[102:105], v[154:157], v[194:197], v[102:105]
	v_mfma_f32_16x16x32_bf16 v[90:93], v[146:149], v[212:215], v[90:93]
	v_mfma_f32_16x16x32_bf16 v[86:89], v[154:157], v[212:215], v[86:89]
	v_mfma_f32_16x16x32_bf16 v[130:133], v[150:153], v[182:185], v[130:133]
	v_mfma_f32_16x16x32_bf16 v[126:129], v[158:161], v[182:185], v[126:129]
	v_mfma_f32_16x16x32_bf16 v[122:125], v[150:153], v[190:193], v[122:125]
	v_mfma_f32_16x16x32_bf16 v[118:121], v[158:161], v[190:193], v[118:121]
	v_mfma_f32_16x16x32_bf16 v[106:109], v[150:153], v[198:201], v[106:109]
	v_mfma_f32_16x16x32_bf16 v[102:105], v[158:161], v[198:201], v[102:105]
	v_mfma_f32_16x16x32_bf16 v[90:93], v[150:153], v[216:219], v[90:93]
	v_mfma_f32_16x16x32_bf16 v[86:89], v[158:161], v[216:219], v[86:89]
	s_setprio 0
	s_setprio 1
	v_mfma_f32_16x16x32_bf16 v[114:117], v[162:165], v[178:181], v[114:117]
	v_mfma_f32_16x16x32_bf16 v[110:113], v[170:173], v[178:181], v[110:113]
	v_mfma_f32_16x16x32_bf16 v[98:101], v[162:165], v[186:189], v[98:101]
	v_mfma_f32_16x16x32_bf16 v[94:97], v[170:173], v[186:189], v[94:97]
	v_mfma_f32_16x16x32_bf16 v[82:85], v[162:165], v[194:197], v[82:85]
	v_mfma_f32_16x16x32_bf16 v[78:81], v[170:173], v[194:197], v[78:81]
	v_mfma_f32_16x16x32_bf16 v[74:77], v[162:165], v[212:215], v[74:77]
	v_mfma_f32_16x16x32_bf16 v[70:73], v[170:173], v[212:215], v[70:73]
	v_mfma_f32_16x16x32_bf16 v[114:117], v[166:169], v[182:185], v[114:117]
	v_mfma_f32_16x16x32_bf16 v[110:113], v[174:177], v[182:185], v[110:113]
	v_mfma_f32_16x16x32_bf16 v[98:101], v[166:169], v[190:193], v[98:101]
	v_mfma_f32_16x16x32_bf16 v[94:97], v[174:177], v[190:193], v[94:97]
	v_mfma_f32_16x16x32_bf16 v[82:85], v[166:169], v[198:201], v[82:85]
	v_mfma_f32_16x16x32_bf16 v[78:81], v[174:177], v[198:201], v[78:81]
	v_mfma_f32_16x16x32_bf16 v[74:77], v[166:169], v[216:219], v[74:77]
	v_mfma_f32_16x16x32_bf16 v[70:73], v[174:177], v[216:219], v[70:73]
	s_barrier
; #define PG8_STAGE(bufoff, gbase, voff) do { _Pragma("unroll") for (int _i = 0; _i < 2; ++_i) \
;         __builtin_amdgcn_global_load_lds((const unsigned*)((const char*)(gbase) + (voff)[_i]), (LAS unsigned*)(lds + (bufoff) + ldsw + _i * 8192), 16, 0, 0); } while (0)
; #define PG8_LDA(dst, b, h) do { _Pragma("unroll") for (int m = 0; m < 4; ++m) _Pragma("unroll") for (int k = 0; k < 2; ++k) dst[m][k] = *(const LAS bf16x8*)(lds + PG8_SA(b, h) + aoff + m * 2048 + k * 1024); } while (0)
; #define PG8_LDB(dst, b, h) do { _Pragma("unroll") for (int n = 0; n < 2; ++n) _Pragma("unroll") for (int k = 0; k < 2; ++k) dst[n][k] = *(const LAS bf16x8*)(lds + PG8_SB(b, h) + boff + n * 2048 + k * 1024); } while (0)
; #define PG8_MMA(ai, bj, At, Bt) do { __builtin_amdgcn_s_setprio(1); _Pragma("unroll") for (int m = 0; m < 4; ++m) _Pragma("unroll") for (int n = 0; n < 2; ++n) _Pragma("unroll") for (int k = 0; k < 2; ++k) \
;         acc[ai][bj][m][n] = __builtin_amdgcn_mfma_f32_16x16x32_bf16(Bt[n][k], At[m][k], acc[ai][bj][m][n], 0, 0, 0); __builtin_amdgcn_s_setprio(0); } while (0)
; #define PG8_WAIT_V(n) asm volatile("s_waitcnt vmcnt(" #n ")" ::: "memory")
; #define PG8_WAIT_L(n) asm volatile("s_waitcnt lgkmcnt(" #n ")" ::: "memory")
; #define PG8_BAR __builtin_amdgcn_s_barrier()
; #define PG8_SCHED __builtin_amdgcn_sched_barrier(0)
; template <class Epi, bool SEG>
; __device__ __forceinline__ void gemm_phase(LAS unsigned char* lds, const Gemm g, const int G, const int cidx, const Epi& E) {
;     ...
;             PG8_LDB(B0, 1, 0); PG8_LDB(B1, 1, 1); PG8_SCHED; PG8_LDA(At, 1, 0); PG8_STAGE(PG8_SA(0, 1), a2 + hstepA, voffA);
;             PG8_WAIT_V(8); PG8_WAIT_L(0); PG8_BAR; PG8_MMA(0, 0, At, B0); PG8_MMA(0, 1, At, B1); PG8_BAR; PG8_SCHED;
;             PG8_LDA(At, 1, 1); PG8_STAGE(PG8_SB(1, 0), b3, voffB); PG8_STAGE(PG8_SB(1, 1), b3 + hstepB, voffB); PG8_STAGE(PG8_SA(1, 0), a3, voffA);
;             PG8_WAIT_V(8); PG8_WAIT_L(0); PG8_BAR; PG8_MMA(1, 0, At, B0); PG8_MMA(1, 1, At, B1); PG8_BAR; PG8_SCHED;
;         }
;         if (wr == 0) PG8_BAR;
	s_setprio 0
	s_add_i32 s22, s64, s39
	v_lshl_add_u64 v[220:221], v[220:221], 0, s[28:29]
	s_mov_b32 m0, s22
	ds_read_b128 v[178:181], v144 offset:49152
	ds_read_b128 v[182:185], v144 offset:50176
	ds_read_b128 v[186:189], v144 offset:51200
	ds_read_b128 v[190:193], v144 offset:52224
	ds_read_b128 v[194:197], v144 offset:53248
	ds_read_b128 v[198:201], v144 offset:54272
	ds_read_b128 v[212:215], v144 offset:55296
	ds_read_b128 v[216:219], v144 offset:56320
	global_load_lds_dwordx4 v[220:221], off
	v_lshl_add_u64 v[220:221], v[222:223], 0, s[28:29]
	s_add_i32 m0, s22, 0x2000
	s_add_i32 s22, s65, s39
	global_load_lds_dwordx4 v[220:221], off
	v_lshl_add_u64 v[220:221], v[224:225], 0, s[28:29]
	s_mov_b32 m0, s22
	s_nop 0
	global_load_lds_dwordx4 v[220:221], off
	v_lshl_add_u64 v[220:221], v[226:227], 0, s[28:29]
	s_add_i32 m0, s22, 0x2000
	s_nop 0
	global_load_lds_dwordx4 v[220:221], off
	v_lshl_add_u64 v[220:221], v[228:229], 0, s[28:29]
	s_mov_b32 m0, s55
	s_nop 0
	global_load_lds_dwordx4 v[220:221], off
	v_lshl_add_u64 v[220:221], v[244:245], 0, s[28:29]
	s_mov_b32 m0, s56
	s_nop 0
	global_load_lds_dwordx4 v[220:221], off
	s_waitcnt vmcnt(8)
	s_waitcnt lgkmcnt(0)
	s_setprio 1
	s_barrier
	v_mfma_f32_16x16x32_bf16 v[66:69], v[146:149], v[178:181], v[66:69]
	v_mfma_f32_16x16x32_bf16 v[62:65], v[154:157], v[178:181], v[62:65]
	v_mfma_f32_16x16x32_bf16 v[58:61], v[146:149], v[186:189], v[58:61]
	v_mfma_f32_16x16x32_bf16 v[54:57], v[154:157], v[186:189], v[54:57]
	v_mfma_f32_16x16x32_bf16 v[42:45], v[146:149], v[194:197], v[42:45]
	v_mfma_f32_16x16x32_bf16 v[38:41], v[154:157], v[194:197], v[38:41]
	v_mfma_f32_16x16x32_bf16 v[26:29], v[146:149], v[212:215], v[26:29]
	v_mfma_f32_16x16x32_bf16 v[22:25], v[154:157], v[212:215], v[22:25]
	v_mfma_f32_16x16x32_bf16 v[66:69], v[150:153], v[182:185], v[66:69]
	v_mfma_f32_16x16x32_bf16 v[62:65], v[158:161], v[182:185], v[62:65]
	v_mfma_f32_16x16x32_bf16 v[58:61], v[150:153], v[190:193], v[58:61]
	v_mfma_f32_16x16x32_bf16 v[54:57], v[158:161], v[190:193], v[54:57]
	v_mfma_f32_16x16x32_bf16 v[42:45], v[150:153], v[198:201], v[42:45]
	v_mfma_f32_16x16x32_bf16 v[38:41], v[158:161], v[198:201], v[38:41]
	v_mfma_f32_16x16x32_bf16 v[26:29], v[150:153], v[216:219], v[26:29]
	v_mfma_f32_16x16x32_bf16 v[22:25], v[158:161], v[216:219], v[22:25]
	s_setprio 0
	s_setprio 1
	v_mfma_f32_16x16x32_bf16 v[50:53], v[162:165], v[178:181], v[50:53]
	v_mfma_f32_16x16x32_bf16 v[46:49], v[170:173], v[178:181], v[46:49]
	v_mfma_f32_16x16x32_bf16 v[34:37], v[162:165], v[186:189], v[34:37]
	v_mfma_f32_16x16x32_bf16 v[30:33], v[170:173], v[186:189], v[30:33]
	v_mfma_f32_16x16x32_bf16 v[18:21], v[162:165], v[194:197], v[18:21]
	v_mfma_f32_16x16x32_bf16 v[10:13], v[170:173], v[194:197], v[10:13]
	v_mfma_f32_16x16x32_bf16 v[6:9], v[162:165], v[212:215], v[6:9]
	v_mfma_f32_16x16x32_bf16 v[2:5], v[170:173], v[212:215], v[2:5]
	v_mfma_f32_16x16x32_bf16 v[50:53], v[166:169], v[182:185], v[50:53]
	v_mfma_f32_16x16x32_bf16 v[46:49], v[174:177], v[182:185], v[46:49]
	v_mfma_f32_16x16x32_bf16 v[34:37], v[166:169], v[190:193], v[34:37]
	v_mfma_f32_16x16x32_bf16 v[30:33], v[174:177], v[190:193], v[30:33]
	v_mfma_f32_16x16x32_bf16 v[18:21], v[166:169], v[198:201], v[18:21]
	v_mfma_f32_16x16x32_bf16 v[10:13], v[174:177], v[198:201], v[10:13]
	v_mfma_f32_16x16x32_bf16 v[6:9], v[166:169], v[216:219], v[6:9]
	v_mfma_f32_16x16x32_bf16 v[2:5], v[174:177], v[216:219], v[2:5]
	s_barrier
	s_setprio 0
	s_add_u32 s61, s61, 0x100
	s_addc_u32 s62, s62, 0
	s_cmp_ge_u32 s63, s53
	s_mov_b64 s[22:23], s[40:41]
	s_mov_b32 s42, s63
	s_cbranch_scc0 .LBB0_1060
	s_and_b64 vcc, exec, s[16:17]
	s_cbranch_vccz .LBB0_1063
	s_barrier
